# P1/P5/P6 K-loops: LDS-DMA issues interleaved with ds_reads in every load segment (dependency-aware reorder)
# speedup vs baseline: 1.0004x; 1.0004x over previous
; #define PG8_STAGE(bufoff, gbase, voff) do { _Pragma("unroll") for (int _i = 0; _i < 2; ++_i) \
;         __builtin_amdgcn_global_load_lds((const unsigned*)((const char*)(gbase) + (voff)[_i]), (PG8_LAS unsigned*)(lds + (bufoff) + ldsw + _i * 8192), 16, 0, 0); } while (0)
; #define PG8_LDA(dst, b, h) do { _Pragma("unroll") for (int m = 0; m < 4; ++m) _Pragma("unroll") for (int k = 0; k < 2; ++k) dst[m][k] = *(const PG8_LAS bf16x8*)(lds + PG8_SA(b, h) + aoff + m * 2048 + k * 1024); } while (0)
; #define PG8_LDB(dst, b, h) do { _Pragma("unroll") for (int n = 0; n < 2; ++n) _Pragma("unroll") for (int k = 0; k < 2; ++k) dst[n][k] = *(const PG8_LAS bf16x8*)(lds + PG8_SB(b, h) + boff + n * 2048 + k * 1024); } while (0)
; #define PG8_MMA(ai, bj, At, Bt) do { __builtin_amdgcn_s_setprio(1); _Pragma("unroll") for (int m = 0; m < 4; ++m) _Pragma("unroll") for (int n = 0; n < 2; ++n) _Pragma("unroll") for (int k = 0; k < 2; ++k) \
;         acc[ai][bj][m][n] = __builtin_amdgcn_mfma_f32_16x16x32_bf16(Bt[n][k], At[m][k], acc[ai][bj][m][n], 0, 0, 0); __builtin_amdgcn_s_setprio(0); } while (0)
; #define PG8_WAIT_V(n) asm volatile("s_waitcnt vmcnt(" #n ")" ::: "memory")
; #define PG8_WAIT_L(n) asm volatile("s_waitcnt lgkmcnt(" #n ")" ::: "memory")
; #define PG8_BAR __builtin_amdgcn_s_barrier()
; #define PG8_SCHED __builtin_amdgcn_sched_barrier(0)
; template <class Epi, class Sched, bool ALIGN_EPI>
; __device__ __forceinline__ void gemm_phase(PG8_LAS unsigned char* lds, const Gemm g, const Sched& S, const Epi& E) {
;     ...
;             PG8_LDB(B0, 0, 0); PG8_LDB(B1, 0, 1); PG8_SCHED; PG8_LDA(At, 0, 0); PG8_STAGE(PG8_SA(1, 1), a1 + hstepA, voffA);
;             PG8_WAIT_V(8); PG8_WAIT_L(0); PG8_BAR; PG8_MMA(0, 0, At, B0); PG8_MMA(0, 1, At, B1); PG8_BAR; PG8_SCHED;
;             PG8_LDA(At, 0, 1); PG8_STAGE(PG8_SB(0, 0), b2, voffB); PG8_STAGE(PG8_SB(0, 1), b2 + hstepB, voffB); PG8_STAGE(PG8_SA(0, 0), a2, voffA);
;             PG8_WAIT_V(8); PG8_WAIT_L(0); PG8_BAR; PG8_MMA(1, 0, At, B0); PG8_MMA(1, 1, At, B1); PG8_BAR; PG8_SCHED;
.LBB0_403:
	ds_read_b128 v[152:155], v166
	ds_read_b128 v[172:175], v166 offset:1024
	ds_read_b128 v[176:179], v166 offset:2048
	ds_read_b128 v[180:183], v166 offset:3072
	ds_read_b128 v[184:187], v167
	ds_read_b128 v[188:191], v167 offset:1024
	s_add_u32 s23, s24, 0xfff80080
	s_addc_u32 s26, s25, -1
	s_cmp_eq_u32 s17, 28
	s_cselect_b32 s29, s19, s26
	s_cselect_b32 s28, s18, s23
	s_cselect_b32 s27, s21, s15
	s_cselect_b32 s26, s20, s5
	v_lshl_add_u64 v[156:157], s[24:25], 0, v[140:141]
	s_add_i32 m0, s34, 0xc000
	s_nop 0
	global_load_lds_dwordx4 v[156:157], off
	ds_read_b128 v[192:195], v167 offset:2048
	ds_read_b128 v[196:199], v167 offset:3072
	ds_read_b128 v[200:203], v168
	ds_read_b128 v[204:207], v168 offset:1024
	ds_read_b128 v[208:211], v168 offset:2048
	ds_read_b128 v[212:215], v168 offset:3072
	v_lshl_add_u64 v[156:157], s[24:25], 0, v[142:143]
	s_add_i32 m0, s34, 0xe000
	s_nop 0
	global_load_lds_dwordx4 v[156:157], off
	ds_read_b128 v[216:219], v168 offset:4096
	ds_read_b128 v[220:223], v168 offset:5120
	ds_read_b128 v[224:227], v168 offset:6144
	ds_read_b128 v[228:231], v168 offset:7168
	s_waitcnt vmcnt(8)
	s_waitcnt lgkmcnt(0)
	s_barrier
	s_setprio 1
	s_waitcnt lgkmcnt(0)
	v_mfma_f32_16x16x32_bf16 v[126:129], v[152:155], v[200:203], v[126:129]
	v_mfma_f32_16x16x32_bf16 v[126:129], v[172:175], v[204:207], v[126:129]
	v_mfma_f32_16x16x32_bf16 v[122:125], v[180:183], v[204:207], v[122:125]
	v_mfma_f32_16x16x32_bf16 v[122:125], v[176:179], v[200:203], v[122:125]
	v_mfma_f32_16x16x32_bf16 v[106:109], v[176:179], v[208:211], v[106:109]
	v_mfma_f32_16x16x32_bf16 v[106:109], v[180:183], v[212:215], v[106:109]
	v_mfma_f32_16x16x32_bf16 v[110:113], v[172:175], v[212:215], v[110:113]
	v_mfma_f32_16x16x32_bf16 v[110:113], v[152:155], v[208:211], v[110:113]
	v_mfma_f32_16x16x32_bf16 v[94:97], v[152:155], v[216:219], v[94:97]
	v_mfma_f32_16x16x32_bf16 v[94:97], v[172:175], v[220:223], v[94:97]
	v_mfma_f32_16x16x32_bf16 v[90:93], v[180:183], v[220:223], v[90:93]
	v_mfma_f32_16x16x32_bf16 v[90:93], v[176:179], v[216:219], v[90:93]
	v_mfma_f32_16x16x32_bf16 v[74:77], v[176:179], v[224:227], v[74:77]
	v_mfma_f32_16x16x32_bf16 v[74:77], v[180:183], v[228:231], v[74:77]
	v_mfma_f32_16x16x32_bf16 v[78:81], v[172:175], v[228:231], v[78:81]
	v_mfma_f32_16x16x32_bf16 v[78:81], v[152:155], v[224:227], v[78:81]
	s_setprio 0
	s_setprio 1
	v_mfma_f32_16x16x32_bf16 v[118:121], v[184:187], v[200:203], v[118:121]
	v_mfma_f32_16x16x32_bf16 v[118:121], v[188:191], v[204:207], v[118:121]
	v_mfma_f32_16x16x32_bf16 v[114:117], v[196:199], v[204:207], v[114:117]
	v_mfma_f32_16x16x32_bf16 v[114:117], v[192:195], v[200:203], v[114:117]
	v_mfma_f32_16x16x32_bf16 v[98:101], v[192:195], v[208:211], v[98:101]
	v_mfma_f32_16x16x32_bf16 v[98:101], v[196:199], v[212:215], v[98:101]
	v_mfma_f32_16x16x32_bf16 v[102:105], v[188:191], v[212:215], v[102:105]
	v_mfma_f32_16x16x32_bf16 v[102:105], v[184:187], v[208:211], v[102:105]
	v_mfma_f32_16x16x32_bf16 v[86:89], v[184:187], v[216:219], v[86:89]
	v_mfma_f32_16x16x32_bf16 v[86:89], v[188:191], v[220:223], v[86:89]
	v_mfma_f32_16x16x32_bf16 v[82:85], v[196:199], v[220:223], v[82:85]
	v_mfma_f32_16x16x32_bf16 v[82:85], v[192:195], v[216:219], v[82:85]
	v_mfma_f32_16x16x32_bf16 v[66:69], v[192:195], v[224:227], v[66:69]
	v_mfma_f32_16x16x32_bf16 v[66:69], v[196:199], v[228:231], v[66:69]
	v_mfma_f32_16x16x32_bf16 v[70:73], v[188:191], v[228:231], v[70:73]
	v_mfma_f32_16x16x32_bf16 v[70:73], v[184:187], v[224:227], v[70:73]
	s_setprio 0
	s_barrier
	ds_read_b128 v[200:203], v168 offset:16384
	ds_read_b128 v[204:207], v168 offset:17408
	s_add_i32 s23, s45, s3
	v_lshl_add_u64 v[156:157], s[26:27], 0, v[134:135]
	s_mov_b32 m0, s23
	s_nop 0
	global_load_lds_dwordx4 v[156:157], off
	ds_read_b128 v[208:211], v168 offset:18432
	ds_read_b128 v[212:215], v168 offset:19456
	s_add_i32 m0, s23, 0x2000
	v_lshl_add_u64 v[232:233], s[26:27], 0, v[130:131]
	global_load_lds_dwordx4 v[232:233], off
	ds_read_b128 v[216:219], v168 offset:20480
	ds_read_b128 v[220:223], v168 offset:21504
	s_add_u32 s48, s26, 0x80000
	s_addc_u32 s49, s27, 0
	s_add_i32 s23, s46, s3
	v_lshl_add_u64 v[234:235], s[48:49], 0, v[134:135]
	s_mov_b32 m0, s23
	s_nop 0
	global_load_lds_dwordx4 v[234:235], off
	ds_read_b128 v[224:227], v168 offset:22528
	ds_read_b128 v[228:231], v168 offset:23552
	v_lshl_add_u64 v[234:235], s[48:49], 0, v[130:131]
	s_add_i32 m0, s23, 0x2000
	s_nop 0
	global_load_lds_dwordx4 v[234:235], off
	v_lshl_add_u64 v[234:235], s[28:29], 0, v[136:137]
	s_mov_b32 m0, s34
	s_nop 0
	global_load_lds_dwordx4 v[234:235], off
	v_lshl_add_u64 v[236:237], s[28:29], 0, v[132:133]
	s_mov_b32 m0, s35
	s_nop 0
	global_load_lds_dwordx4 v[236:237], off
	s_waitcnt vmcnt(8)
	s_waitcnt lgkmcnt(0)
	s_barrier
; #define PG8_STAGE(bufoff, gbase, voff) do { _Pragma("unroll") for (int _i = 0; _i < 2; ++_i) \
;         __builtin_amdgcn_global_load_lds((const unsigned*)((const char*)(gbase) + (voff)[_i]), (PG8_LAS unsigned*)(lds + (bufoff) + ldsw + _i * 8192), 16, 0, 0); } while (0)
; #define PG8_LDA(dst, b, h) do { _Pragma("unroll") for (int m = 0; m < 4; ++m) _Pragma("unroll") for (int k = 0; k < 2; ++k) dst[m][k] = *(const PG8_LAS bf16x8*)(lds + PG8_SA(b, h) + aoff + m * 2048 + k * 1024); } while (0)
; #define PG8_LDB(dst, b, h) do { _Pragma("unroll") for (int n = 0; n < 2; ++n) _Pragma("unroll") for (int k = 0; k < 2; ++k) dst[n][k] = *(const PG8_LAS bf16x8*)(lds + PG8_SB(b, h) + boff + n * 2048 + k * 1024); } while (0)
; #define PG8_MMA(ai, bj, At, Bt) do { __builtin_amdgcn_s_setprio(1); _Pragma("unroll") for (int m = 0; m < 4; ++m) _Pragma("unroll") for (int n = 0; n < 2; ++n) _Pragma("unroll") for (int k = 0; k < 2; ++k) \
;         acc[ai][bj][m][n] = __builtin_amdgcn_mfma_f32_16x16x32_bf16(Bt[n][k], At[m][k], acc[ai][bj][m][n], 0, 0, 0); __builtin_amdgcn_s_setprio(0); } while (0)
; #define PG8_WAIT_V(n) asm volatile("s_waitcnt vmcnt(" #n ")" ::: "memory")
; #define PG8_WAIT_L(n) asm volatile("s_waitcnt lgkmcnt(" #n ")" ::: "memory")
; #define PG8_BAR __builtin_amdgcn_s_barrier()
; #define PG8_SCHED __builtin_amdgcn_sched_barrier(0)
; template <class Epi, class Sched, bool ALIGN_EPI>
; __device__ __forceinline__ void gemm_phase(PG8_LAS unsigned char* lds, const Gemm g, const Sched& S, const Epi& E) {
;     ...
;             PG8_WAIT_V(8); PG8_WAIT_L(0); PG8_BAR; PG8_MMA(1, 0, At, B0); PG8_MMA(1, 1, At, B1); PG8_BAR; PG8_SCHED;
;             PG8_LDB(B0, 1, 0); PG8_LDB(B1, 1, 1); PG8_SCHED; PG8_LDA(At, 1, 0); PG8_STAGE(PG8_SA(0, 1), a2 + hstepA, voffA);
;             PG8_WAIT_V(8); PG8_WAIT_L(0); PG8_BAR; PG8_MMA(0, 0, At, B0); PG8_MMA(0, 1, At, B1); PG8_BAR; PG8_SCHED;
	s_setprio 1
	s_waitcnt lgkmcnt(0)
	v_mfma_f32_16x16x32_bf16 v[62:65], v[152:155], v[200:203], v[62:65]
	v_mfma_f32_16x16x32_bf16 v[62:65], v[172:175], v[204:207], v[62:65]
	v_mfma_f32_16x16x32_bf16 v[58:61], v[180:183], v[204:207], v[58:61]
	v_mfma_f32_16x16x32_bf16 v[58:61], v[176:179], v[200:203], v[58:61]
	v_mfma_f32_16x16x32_bf16 v[42:45], v[176:179], v[208:211], v[42:45]
	v_mfma_f32_16x16x32_bf16 v[42:45], v[180:183], v[212:215], v[42:45]
	v_mfma_f32_16x16x32_bf16 v[46:49], v[172:175], v[212:215], v[46:49]
	v_mfma_f32_16x16x32_bf16 v[46:49], v[152:155], v[208:211], v[46:49]
	v_mfma_f32_16x16x32_bf16 v[30:33], v[152:155], v[216:219], v[30:33]
	v_mfma_f32_16x16x32_bf16 v[30:33], v[172:175], v[220:223], v[30:33]
	v_mfma_f32_16x16x32_bf16 v[26:29], v[180:183], v[220:223], v[26:29]
	v_mfma_f32_16x16x32_bf16 v[26:29], v[176:179], v[216:219], v[26:29]
	v_mfma_f32_16x16x32_bf16 v[10:13], v[176:179], v[224:227], v[10:13]
	v_mfma_f32_16x16x32_bf16 v[10:13], v[180:183], v[228:231], v[10:13]
	v_mfma_f32_16x16x32_bf16 v[14:17], v[172:175], v[228:231], v[14:17]
	v_mfma_f32_16x16x32_bf16 v[14:17], v[152:155], v[224:227], v[14:17]
	s_setprio 0
	s_setprio 1
	v_mfma_f32_16x16x32_bf16 v[54:57], v[184:187], v[200:203], v[54:57]
	v_mfma_f32_16x16x32_bf16 v[54:57], v[188:191], v[204:207], v[54:57]
	v_mfma_f32_16x16x32_bf16 v[50:53], v[196:199], v[204:207], v[50:53]
	v_mfma_f32_16x16x32_bf16 v[50:53], v[192:195], v[200:203], v[50:53]
	v_mfma_f32_16x16x32_bf16 v[34:37], v[192:195], v[208:211], v[34:37]
	v_mfma_f32_16x16x32_bf16 v[34:37], v[196:199], v[212:215], v[34:37]
	v_mfma_f32_16x16x32_bf16 v[38:41], v[188:191], v[212:215], v[38:41]
	v_mfma_f32_16x16x32_bf16 v[38:41], v[184:187], v[208:211], v[38:41]
	v_mfma_f32_16x16x32_bf16 v[22:25], v[184:187], v[216:219], v[22:25]
	v_mfma_f32_16x16x32_bf16 v[22:25], v[188:191], v[220:223], v[22:25]
	v_mfma_f32_16x16x32_bf16 v[18:21], v[196:199], v[220:223], v[18:21]
	v_mfma_f32_16x16x32_bf16 v[18:21], v[192:195], v[216:219], v[18:21]
	v_mfma_f32_16x16x32_bf16 v[2:5], v[192:195], v[224:227], v[2:5]
	v_mfma_f32_16x16x32_bf16 v[2:5], v[196:199], v[228:231], v[2:5]
	v_mfma_f32_16x16x32_bf16 v[6:9], v[188:191], v[228:231], v[6:9]
	v_mfma_f32_16x16x32_bf16 v[6:9], v[184:187], v[224:227], v[6:9]
	s_setprio 0
	s_barrier
	s_add_i32 s23, 0, 0x18000
	v_add_u32_e32 v149, s23, v159
	ds_read_b128 v[152:155], v149
	ds_read_b128 v[172:175], v149 offset:1024
	ds_read_b128 v[176:179], v149 offset:2048
	ds_read_b128 v[180:183], v149 offset:3072
	s_add_i32 s48, 0, 0x1c000
	v_add_u32_e32 v149, s48, v159
	ds_read_b128 v[184:187], v149
	ds_read_b128 v[188:191], v149 offset:1024
	s_add_u32 s28, s28, 0x80000
	s_addc_u32 s29, s29, 0
	s_mov_b32 m0, s36
	v_lshl_add_u64 v[238:239], s[28:29], 0, v[136:137]
	global_load_lds_dwordx4 v[238:239], off
	ds_read_b128 v[192:195], v149 offset:2048
	ds_read_b128 v[196:199], v149 offset:3072
	ds_read_b128 v[200:203], v168 offset:32768
	ds_read_b128 v[204:207], v168 offset:33792
	ds_read_b128 v[208:211], v168 offset:34816
	ds_read_b128 v[212:215], v168 offset:35840
	v_lshl_add_u64 v[238:239], s[28:29], 0, v[132:133]
	s_mov_b32 m0, s37
	s_nop 0
	global_load_lds_dwordx4 v[238:239], off
	ds_read_b128 v[216:219], v168 offset:36864
	ds_read_b128 v[220:223], v168 offset:37888
	ds_read_b128 v[224:227], v168 offset:38912
	ds_read_b128 v[228:231], v168 offset:39936
	s_waitcnt vmcnt(8)
	s_waitcnt lgkmcnt(0)
	s_barrier
	s_setprio 1
	s_waitcnt lgkmcnt(0)
	v_mfma_f32_16x16x32_bf16 v[126:129], v[152:155], v[200:203], v[126:129]
	v_mfma_f32_16x16x32_bf16 v[126:129], v[172:175], v[204:207], v[126:129]
	v_mfma_f32_16x16x32_bf16 v[122:125], v[180:183], v[204:207], v[122:125]
	v_mfma_f32_16x16x32_bf16 v[122:125], v[176:179], v[200:203], v[122:125]
	v_mfma_f32_16x16x32_bf16 v[106:109], v[176:179], v[208:211], v[106:109]
	v_mfma_f32_16x16x32_bf16 v[106:109], v[180:183], v[212:215], v[106:109]
	v_mfma_f32_16x16x32_bf16 v[110:113], v[172:175], v[212:215], v[110:113]
	v_mfma_f32_16x16x32_bf16 v[110:113], v[152:155], v[208:211], v[110:113]
	v_mfma_f32_16x16x32_bf16 v[94:97], v[152:155], v[216:219], v[94:97]
	v_mfma_f32_16x16x32_bf16 v[94:97], v[172:175], v[220:223], v[94:97]
	v_mfma_f32_16x16x32_bf16 v[90:93], v[180:183], v[220:223], v[90:93]
	v_mfma_f32_16x16x32_bf16 v[90:93], v[176:179], v[216:219], v[90:93]
	v_mfma_f32_16x16x32_bf16 v[74:77], v[176:179], v[224:227], v[74:77]
	v_mfma_f32_16x16x32_bf16 v[74:77], v[180:183], v[228:231], v[74:77]
	v_mfma_f32_16x16x32_bf16 v[78:81], v[172:175], v[228:231], v[78:81]
	v_mfma_f32_16x16x32_bf16 v[78:81], v[152:155], v[224:227], v[78:81]
	s_setprio 0
	s_setprio 1
	v_mfma_f32_16x16x32_bf16 v[118:121], v[184:187], v[200:203], v[118:121]
	v_mfma_f32_16x16x32_bf16 v[118:121], v[188:191], v[204:207], v[118:121]
	v_mfma_f32_16x16x32_bf16 v[114:117], v[196:199], v[204:207], v[114:117]
	v_mfma_f32_16x16x32_bf16 v[114:117], v[192:195], v[200:203], v[114:117]
	v_mfma_f32_16x16x32_bf16 v[98:101], v[192:195], v[208:211], v[98:101]
	v_mfma_f32_16x16x32_bf16 v[98:101], v[196:199], v[212:215], v[98:101]
	v_mfma_f32_16x16x32_bf16 v[102:105], v[188:191], v[212:215], v[102:105]
	v_mfma_f32_16x16x32_bf16 v[102:105], v[184:187], v[208:211], v[102:105]
	v_mfma_f32_16x16x32_bf16 v[86:89], v[184:187], v[216:219], v[86:89]
	v_mfma_f32_16x16x32_bf16 v[86:89], v[188:191], v[220:223], v[86:89]
	v_mfma_f32_16x16x32_bf16 v[82:85], v[196:199], v[220:223], v[82:85]
	v_mfma_f32_16x16x32_bf16 v[82:85], v[192:195], v[216:219], v[82:85]
	v_mfma_f32_16x16x32_bf16 v[66:69], v[192:195], v[224:227], v[66:69]
	v_mfma_f32_16x16x32_bf16 v[66:69], v[196:199], v[228:231], v[66:69]
	v_mfma_f32_16x16x32_bf16 v[70:73], v[188:191], v[228:231], v[70:73]
	v_mfma_f32_16x16x32_bf16 v[70:73], v[184:187], v[224:227], v[70:73]
	s_setprio 0
	s_barrier
; #define PG8_STAGE(bufoff, gbase, voff) do { _Pragma("unroll") for (int _i = 0; _i < 2; ++_i) \
;         __builtin_amdgcn_global_load_lds((const unsigned*)((const char*)(gbase) + (voff)[_i]), (PG8_LAS unsigned*)(lds + (bufoff) + ldsw + _i * 8192), 16, 0, 0); } while (0)
; #define PG8_LDA(dst, b, h) do { _Pragma("unroll") for (int m = 0; m < 4; ++m) _Pragma("unroll") for (int k = 0; k < 2; ++k) dst[m][k] = *(const PG8_LAS bf16x8*)(lds + PG8_SA(b, h) + aoff + m * 2048 + k * 1024); } while (0)
; #define PG8_MMA(ai, bj, At, Bt) do { __builtin_amdgcn_s_setprio(1); _Pragma("unroll") for (int m = 0; m < 4; ++m) _Pragma("unroll") for (int n = 0; n < 2; ++n) _Pragma("unroll") for (int k = 0; k < 2; ++k) \
;         acc[ai][bj][m][n] = __builtin_amdgcn_mfma_f32_16x16x32_bf16(Bt[n][k], At[m][k], acc[ai][bj][m][n], 0, 0, 0); __builtin_amdgcn_s_setprio(0); } while (0)
; #define PG8_WAIT_V(n) asm volatile("s_waitcnt vmcnt(" #n ")" ::: "memory")
; #define PG8_WAIT_L(n) asm volatile("s_waitcnt lgkmcnt(" #n ")" ::: "memory")
; #define PG8_BAR __builtin_amdgcn_s_barrier()
; #define PG8_SCHED __builtin_amdgcn_sched_barrier(0)
; template <class Epi, class Sched, bool ALIGN_EPI>
; __device__ __forceinline__ void gemm_phase(PG8_LAS unsigned char* lds, const Gemm g, const Sched& S, const Epi& E) {
;     ...
;             PG8_LDA(At, 1, 1); PG8_STAGE(PG8_SB(1, 0), b3, voffB); PG8_STAGE(PG8_SB(1, 1), b3 + hstepB, voffB); PG8_STAGE(PG8_SA(1, 0), a3, voffA);
;             PG8_WAIT_V(8); PG8_WAIT_L(0); PG8_BAR; PG8_MMA(1, 0, At, B0); PG8_MMA(1, 1, At, B1); PG8_BAR; PG8_SCHED;
;         }
	ds_read_b128 v[200:203], v168 offset:49152
	ds_read_b128 v[204:207], v168 offset:50176
	s_add_i32 s23, s23, s3
	v_lshl_add_u64 v[156:157], v[156:157], 0, s[8:9]
	s_mov_b32 m0, s23
	s_nop 0
	global_load_lds_dwordx4 v[156:157], off
	ds_read_b128 v[208:211], v168 offset:51200
	ds_read_b128 v[212:215], v168 offset:52224
	s_add_i32 m0, s23, 0x2000
	v_lshl_add_u64 v[156:157], v[232:233], 0, s[8:9]
	global_load_lds_dwordx4 v[156:157], off
	ds_read_b128 v[216:219], v168 offset:53248
	ds_read_b128 v[220:223], v168 offset:54272
	s_add_u32 s26, s26, 0x80080
	s_addc_u32 s27, s27, 0
	s_add_i32 s23, s48, s3
	v_lshl_add_u64 v[156:157], s[26:27], 0, v[134:135]
	s_mov_b32 m0, s23
	s_nop 0
	global_load_lds_dwordx4 v[156:157], off
	ds_read_b128 v[224:227], v168 offset:55296
	ds_read_b128 v[228:231], v168 offset:56320
	v_lshl_add_u64 v[156:157], s[26:27], 0, v[130:131]
	s_add_i32 m0, s23, 0x2000
	s_nop 0
	global_load_lds_dwordx4 v[156:157], off
	v_lshl_add_u64 v[156:157], v[234:235], 0, s[8:9]
	s_mov_b32 m0, s42
	s_nop 0
	global_load_lds_dwordx4 v[156:157], off
	v_lshl_add_u64 v[156:157], v[236:237], 0, s[8:9]
	s_mov_b32 m0, s43
	s_nop 0
	global_load_lds_dwordx4 v[156:157], off
	s_waitcnt vmcnt(8)
	s_waitcnt lgkmcnt(0)
	s_barrier
	s_setprio 1
	s_waitcnt lgkmcnt(0)
	v_mfma_f32_16x16x32_bf16 v[62:65], v[152:155], v[200:203], v[62:65]
	v_mfma_f32_16x16x32_bf16 v[62:65], v[172:175], v[204:207], v[62:65]
	v_mfma_f32_16x16x32_bf16 v[58:61], v[180:183], v[204:207], v[58:61]
	v_mfma_f32_16x16x32_bf16 v[58:61], v[176:179], v[200:203], v[58:61]
	v_mfma_f32_16x16x32_bf16 v[42:45], v[176:179], v[208:211], v[42:45]
	v_mfma_f32_16x16x32_bf16 v[42:45], v[180:183], v[212:215], v[42:45]
	v_mfma_f32_16x16x32_bf16 v[46:49], v[172:175], v[212:215], v[46:49]
	v_mfma_f32_16x16x32_bf16 v[46:49], v[152:155], v[208:211], v[46:49]
	v_mfma_f32_16x16x32_bf16 v[30:33], v[152:155], v[216:219], v[30:33]
	v_mfma_f32_16x16x32_bf16 v[30:33], v[172:175], v[220:223], v[30:33]
	v_mfma_f32_16x16x32_bf16 v[26:29], v[180:183], v[220:223], v[26:29]
	v_mfma_f32_16x16x32_bf16 v[26:29], v[176:179], v[216:219], v[26:29]
	v_mfma_f32_16x16x32_bf16 v[10:13], v[176:179], v[224:227], v[10:13]
	v_mfma_f32_16x16x32_bf16 v[10:13], v[180:183], v[228:231], v[10:13]
	v_mfma_f32_16x16x32_bf16 v[14:17], v[172:175], v[228:231], v[14:17]
	v_mfma_f32_16x16x32_bf16 v[14:17], v[152:155], v[224:227], v[14:17]
	s_setprio 0
	s_setprio 1
	v_mfma_f32_16x16x32_bf16 v[54:57], v[184:187], v[200:203], v[54:57]
	v_mfma_f32_16x16x32_bf16 v[54:57], v[188:191], v[204:207], v[54:57]
	v_mfma_f32_16x16x32_bf16 v[50:53], v[196:199], v[204:207], v[50:53]
	v_mfma_f32_16x16x32_bf16 v[50:53], v[192:195], v[200:203], v[50:53]
	v_mfma_f32_16x16x32_bf16 v[34:37], v[192:195], v[208:211], v[34:37]
	v_mfma_f32_16x16x32_bf16 v[34:37], v[196:199], v[212:215], v[34:37]
	v_mfma_f32_16x16x32_bf16 v[38:41], v[188:191], v[212:215], v[38:41]
	v_mfma_f32_16x16x32_bf16 v[38:41], v[184:187], v[208:211], v[38:41]
	v_mfma_f32_16x16x32_bf16 v[22:25], v[184:187], v[216:219], v[22:25]
	v_mfma_f32_16x16x32_bf16 v[22:25], v[188:191], v[220:223], v[22:25]
	v_mfma_f32_16x16x32_bf16 v[18:21], v[196:199], v[220:223], v[18:21]
	v_mfma_f32_16x16x32_bf16 v[18:21], v[192:195], v[216:219], v[18:21]
	v_mfma_f32_16x16x32_bf16 v[2:5], v[192:195], v[224:227], v[2:5]
	v_mfma_f32_16x16x32_bf16 v[2:5], v[196:199], v[228:231], v[2:5]
	v_mfma_f32_16x16x32_bf16 v[6:9], v[188:191], v[228:231], v[6:9]
	v_mfma_f32_16x16x32_bf16 v[6:9], v[184:187], v[224:227], v[6:9]
	s_setprio 0
	s_barrier
	s_add_i32 s17, s17, 2
	s_add_u32 s24, s24, 0x100
	s_addc_u32 s25, s25, 0
	s_add_u32 s5, s5, 0x100
	s_addc_u32 s15, s15, 0
	s_cmp_gt_u32 s17, 29
	s_cbranch_scc0 .LBB0_403
	s_and_b64 vcc, exec, s[10:11]
	s_cbranch_vccz .LBB0_406
	s_barrier

; #define PG8_STAGE(bufoff, gbase, voff) do { _Pragma("unroll") for (int _i = 0; _i < 2; ++_i) \
;         __builtin_amdgcn_global_load_lds((const unsigned*)((const char*)(gbase) + (voff)[_i]), (PG8_LAS unsigned*)(lds + (bufoff) + ldsw + _i * 8192), 16, 0, 0); } while (0)
; #define PG8_LDA(dst, b, h) do { _Pragma("unroll") for (int m = 0; m < 4; ++m) _Pragma("unroll") for (int k = 0; k < 2; ++k) dst[m][k] = *(const PG8_LAS bf16x8*)(lds + PG8_SA(b, h) + aoff + m * 2048 + k * 1024); } while (0)
; #define PG8_LDB(dst, b, h) do { _Pragma("unroll") for (int n = 0; n < 2; ++n) _Pragma("unroll") for (int k = 0; k < 2; ++k) dst[n][k] = *(const PG8_LAS bf16x8*)(lds + PG8_SB(b, h) + boff + n * 2048 + k * 1024); } while (0)
; #define PG8_MMA(ai, bj, At, Bt) do { __builtin_amdgcn_s_setprio(1); _Pragma("unroll") for (int m = 0; m < 4; ++m) _Pragma("unroll") for (int n = 0; n < 2; ++n) _Pragma("unroll") for (int k = 0; k < 2; ++k) \
;         acc[ai][bj][m][n] = __builtin_amdgcn_mfma_f32_16x16x32_bf16(Bt[n][k], At[m][k], acc[ai][bj][m][n], 0, 0, 0); __builtin_amdgcn_s_setprio(0); } while (0)
; #define PG8_WAIT_V(n) asm volatile("s_waitcnt vmcnt(" #n ")" ::: "memory")
; #define PG8_WAIT_L(n) asm volatile("s_waitcnt lgkmcnt(" #n ")" ::: "memory")
; #define PG8_BAR __builtin_amdgcn_s_barrier()
; #define PG8_SCHED __builtin_amdgcn_sched_barrier(0)
; template <class Epi, class Sched, bool ALIGN_EPI>
; __device__ __forceinline__ void gemm_phase(PG8_LAS unsigned char* lds, const Gemm g, const Sched& S, const Epi& E) {
;     ...
;             const char* a1 = cA + (size_t)(t + 1) * kstepA;
;             const char* a2 = last ? nA : cA + (size_t)(t + 2) * kstepA; const char* b2 = last ? nB : cB + (size_t)(t + 2) * kstep;
;             const char* a3 = a2 + kstepA; const char* b3 = b2 + kstep;
;             PG8_LDB(B0, 0, 0); PG8_LDB(B1, 0, 1); PG8_SCHED; PG8_LDA(At, 0, 0); PG8_STAGE(PG8_SA(1, 1), a1 + hstepA, voffA);
;             PG8_WAIT_V(8); PG8_WAIT_L(0); PG8_BAR; PG8_MMA(0, 0, At, B0); PG8_MMA(0, 1, At, B1); PG8_BAR; PG8_SCHED;
;             PG8_LDA(At, 0, 1); PG8_STAGE(PG8_SB(0, 0), b2, voffB); PG8_STAGE(PG8_SB(0, 1), b2 + hstepB, voffB); PG8_STAGE(PG8_SA(0, 0), a2, voffA);
;             PG8_WAIT_V(8); PG8_WAIT_L(0); PG8_BAR; PG8_MMA(1, 0, At, B0); PG8_MMA(1, 1, At, B1); PG8_BAR; PG8_SCHED;
.LBB0_431:
	ds_read_b128 v[150:153], v147
	ds_read_b128 v[154:157], v147 offset:1024
	ds_read_b128 v[158:161], v147 offset:2048
	ds_read_b128 v[162:165], v147 offset:3072
	ds_read_b128 v[166:169], v148
	ds_read_b128 v[170:173], v148 offset:1024
	s_add_u32 s34, s30, 0xfff80080
	s_addc_u32 s35, s31, -1
	s_cmp_eq_u32 s54, 28
	s_cselect_b32 s37, s25, s35
	s_cselect_b32 s36, s24, s34
	s_cselect_b32 s35, s27, s23
	s_cselect_b32 s34, s26, s21
	v_lshl_add_u64 v[142:143], s[30:31], 0, v[138:139]
	s_add_i32 m0, s29, 0xc000
	s_nop 0
	global_load_lds_dwordx4 v[142:143], off
	ds_read_b128 v[174:177], v148 offset:2048
	ds_read_b128 v[178:181], v148 offset:3072
	ds_read_b128 v[182:185], v149
	ds_read_b128 v[186:189], v149 offset:1024
	ds_read_b128 v[190:193], v149 offset:2048
	ds_read_b128 v[194:197], v149 offset:3072
	v_lshl_add_u64 v[142:143], s[30:31], 0, v[140:141]
	s_add_i32 m0, s29, 0xe000
	s_nop 0
	global_load_lds_dwordx4 v[142:143], off
	ds_read_b128 v[198:201], v149 offset:4096
	ds_read_b128 v[202:205], v149 offset:5120
	ds_read_b128 v[206:209], v149 offset:6144
	ds_read_b128 v[210:213], v149 offset:7168
	s_waitcnt vmcnt(8)
	s_waitcnt lgkmcnt(0)
	s_barrier
	s_setprio 1
	s_waitcnt lgkmcnt(0)
	v_mfma_f32_16x16x32_bf16 v[126:129], v[150:153], v[182:185], v[126:129]
	v_mfma_f32_16x16x32_bf16 v[126:129], v[154:157], v[186:189], v[126:129]
	v_mfma_f32_16x16x32_bf16 v[122:125], v[162:165], v[186:189], v[122:125]
	v_mfma_f32_16x16x32_bf16 v[122:125], v[158:161], v[182:185], v[122:125]
	v_mfma_f32_16x16x32_bf16 v[110:113], v[158:161], v[190:193], v[110:113]
	v_mfma_f32_16x16x32_bf16 v[110:113], v[162:165], v[194:197], v[110:113]
	v_mfma_f32_16x16x32_bf16 v[118:121], v[154:157], v[194:197], v[118:121]
	v_mfma_f32_16x16x32_bf16 v[118:121], v[150:153], v[190:193], v[118:121]
	v_mfma_f32_16x16x32_bf16 v[102:105], v[150:153], v[198:201], v[102:105]
	v_mfma_f32_16x16x32_bf16 v[102:105], v[154:157], v[202:205], v[102:105]
	v_mfma_f32_16x16x32_bf16 v[94:97], v[162:165], v[202:205], v[94:97]
	v_mfma_f32_16x16x32_bf16 v[94:97], v[158:161], v[198:201], v[94:97]
	v_mfma_f32_16x16x32_bf16 v[78:81], v[158:161], v[206:209], v[78:81]
	v_mfma_f32_16x16x32_bf16 v[78:81], v[162:165], v[210:213], v[78:81]
	v_mfma_f32_16x16x32_bf16 v[86:89], v[154:157], v[210:213], v[86:89]
	v_mfma_f32_16x16x32_bf16 v[86:89], v[150:153], v[206:209], v[86:89]
	s_setprio 0
	s_setprio 1
	v_mfma_f32_16x16x32_bf16 v[114:117], v[166:169], v[182:185], v[114:117]
	v_mfma_f32_16x16x32_bf16 v[114:117], v[170:173], v[186:189], v[114:117]
	v_mfma_f32_16x16x32_bf16 v[106:109], v[178:181], v[186:189], v[106:109]
	v_mfma_f32_16x16x32_bf16 v[106:109], v[174:177], v[182:185], v[106:109]
	v_mfma_f32_16x16x32_bf16 v[90:93], v[174:177], v[190:193], v[90:93]
	v_mfma_f32_16x16x32_bf16 v[90:93], v[178:181], v[194:197], v[90:93]
	v_mfma_f32_16x16x32_bf16 v[98:101], v[170:173], v[194:197], v[98:101]
	v_mfma_f32_16x16x32_bf16 v[98:101], v[166:169], v[190:193], v[98:101]
	v_mfma_f32_16x16x32_bf16 v[82:85], v[166:169], v[198:201], v[82:85]
	v_mfma_f32_16x16x32_bf16 v[82:85], v[170:173], v[202:205], v[82:85]
	v_mfma_f32_16x16x32_bf16 v[74:77], v[178:181], v[202:205], v[74:77]
	v_mfma_f32_16x16x32_bf16 v[74:77], v[174:177], v[198:201], v[74:77]
	v_mfma_f32_16x16x32_bf16 v[66:69], v[174:177], v[206:209], v[66:69]
	v_mfma_f32_16x16x32_bf16 v[66:69], v[178:181], v[210:213], v[66:69]
	v_mfma_f32_16x16x32_bf16 v[70:73], v[170:173], v[210:213], v[70:73]
	v_mfma_f32_16x16x32_bf16 v[70:73], v[166:169], v[206:209], v[70:73]
	s_setprio 0
	s_barrier
	ds_read_b128 v[182:185], v149 offset:16384
	ds_read_b128 v[186:189], v149 offset:17408
	s_add_i32 s55, s47, s39
	v_lshl_add_u64 v[142:143], s[34:35], 0, v[132:133]
	s_mov_b32 m0, s55
	s_nop 0
	global_load_lds_dwordx4 v[142:143], off
	ds_read_b128 v[190:193], v149 offset:18432
	ds_read_b128 v[194:197], v149 offset:19456
	s_add_i32 m0, s55, 0x2000
	v_lshl_add_u64 v[214:215], s[34:35], 0, v[136:137]
	global_load_lds_dwordx4 v[214:215], off
	ds_read_b128 v[198:201], v149 offset:20480
	ds_read_b128 v[202:205], v149 offset:21504
	s_add_u32 s56, s34, 0x80000
	s_addc_u32 s57, s35, 0
	s_add_i32 s55, s48, s39
	v_lshl_add_u64 v[216:217], s[56:57], 0, v[132:133]
	s_mov_b32 m0, s55
	s_nop 0
	global_load_lds_dwordx4 v[216:217], off
	ds_read_b128 v[206:209], v149 offset:22528
	ds_read_b128 v[210:213], v149 offset:23552
	v_lshl_add_u64 v[216:217], s[56:57], 0, v[136:137]
	s_add_i32 m0, s55, 0x2000
	s_nop 0
	global_load_lds_dwordx4 v[216:217], off
	v_lshl_add_u64 v[216:217], s[36:37], 0, v[130:131]
	s_mov_b32 m0, s29
	s_nop 0
	global_load_lds_dwordx4 v[216:217], off
	v_lshl_add_u64 v[218:219], s[36:37], 0, v[134:135]
	s_mov_b32 m0, s40
	s_nop 0
	global_load_lds_dwordx4 v[218:219], off
	s_waitcnt vmcnt(8)
	s_waitcnt lgkmcnt(0)
	s_barrier
; #define PG8_STAGE(bufoff, gbase, voff) do { _Pragma("unroll") for (int _i = 0; _i < 2; ++_i) \
;         __builtin_amdgcn_global_load_lds((const unsigned*)((const char*)(gbase) + (voff)[_i]), (PG8_LAS unsigned*)(lds + (bufoff) + ldsw + _i * 8192), 16, 0, 0); } while (0)
; #define PG8_LDA(dst, b, h) do { _Pragma("unroll") for (int m = 0; m < 4; ++m) _Pragma("unroll") for (int k = 0; k < 2; ++k) dst[m][k] = *(const PG8_LAS bf16x8*)(lds + PG8_SA(b, h) + aoff + m * 2048 + k * 1024); } while (0)
; #define PG8_LDB(dst, b, h) do { _Pragma("unroll") for (int n = 0; n < 2; ++n) _Pragma("unroll") for (int k = 0; k < 2; ++k) dst[n][k] = *(const PG8_LAS bf16x8*)(lds + PG8_SB(b, h) + boff + n * 2048 + k * 1024); } while (0)
; #define PG8_MMA(ai, bj, At, Bt) do { __builtin_amdgcn_s_setprio(1); _Pragma("unroll") for (int m = 0; m < 4; ++m) _Pragma("unroll") for (int n = 0; n < 2; ++n) _Pragma("unroll") for (int k = 0; k < 2; ++k) \
;         acc[ai][bj][m][n] = __builtin_amdgcn_mfma_f32_16x16x32_bf16(Bt[n][k], At[m][k], acc[ai][bj][m][n], 0, 0, 0); __builtin_amdgcn_s_setprio(0); } while (0)
; #define PG8_WAIT_V(n) asm volatile("s_waitcnt vmcnt(" #n ")" ::: "memory")
; #define PG8_WAIT_L(n) asm volatile("s_waitcnt lgkmcnt(" #n ")" ::: "memory")
; #define PG8_BAR __builtin_amdgcn_s_barrier()
; template <class Epi, class Sched, bool ALIGN_EPI>
; __device__ __forceinline__ void gemm_phase(PG8_LAS unsigned char* lds, const Gemm g, const Sched& S, const Epi& E) {
;     ...
;             PG8_WAIT_V(8); PG8_WAIT_L(0); PG8_BAR; PG8_MMA(0, 0, At, B0); PG8_MMA(0, 1, At, B1); PG8_BAR; PG8_SCHED;
;             PG8_LDA(At, 0, 1); PG8_STAGE(PG8_SB(0, 0), b2, voffB); PG8_STAGE(PG8_SB(0, 1), b2 + hstepB, voffB); PG8_STAGE(PG8_SA(0, 0), a2, voffA);
;             PG8_WAIT_V(8); PG8_WAIT_L(0); PG8_BAR; PG8_MMA(1, 0, At, B0); PG8_MMA(1, 1, At, B1); PG8_BAR; PG8_SCHED;
;             PG8_LDB(B0, 1, 0); PG8_LDB(B1, 1, 1); PG8_SCHED; PG8_LDA(At, 1, 0); PG8_STAGE(PG8_SA(0, 1), a2 + hstepA, voffA);
;             PG8_WAIT_V(8); PG8_WAIT_L(0); PG8_BAR; PG8_MMA(0, 0, At, B0); PG8_MMA(0, 1, At, B1); PG8_BAR; PG8_SCHED;
;             PG8_LDA(At, 1, 1); PG8_STAGE(PG8_SB(1, 0), b3, voffB); PG8_STAGE(PG8_SB(1, 1), b3 + hstepB, voffB); PG8_STAGE(PG8_SA(1, 0), a3, voffA);
;             PG8_WAIT_V(8); PG8_WAIT_L(0); PG8_BAR; PG8_MMA(1, 0, At, B0); PG8_MMA(1, 1, At, B1); PG8_BAR; PG8_SCHED;
	s_setprio 1
	s_waitcnt lgkmcnt(0)
	v_mfma_f32_16x16x32_bf16 v[62:65], v[150:153], v[182:185], v[62:65]
	v_mfma_f32_16x16x32_bf16 v[62:65], v[154:157], v[186:189], v[62:65]
	v_mfma_f32_16x16x32_bf16 v[58:61], v[162:165], v[186:189], v[58:61]
	v_mfma_f32_16x16x32_bf16 v[58:61], v[158:161], v[182:185], v[58:61]
	v_mfma_f32_16x16x32_bf16 v[46:49], v[158:161], v[190:193], v[46:49]
	v_mfma_f32_16x16x32_bf16 v[46:49], v[162:165], v[194:197], v[46:49]
	v_mfma_f32_16x16x32_bf16 v[54:57], v[154:157], v[194:197], v[54:57]
	v_mfma_f32_16x16x32_bf16 v[54:57], v[150:153], v[190:193], v[54:57]
	v_mfma_f32_16x16x32_bf16 v[38:41], v[150:153], v[198:201], v[38:41]
	v_mfma_f32_16x16x32_bf16 v[38:41], v[154:157], v[202:205], v[38:41]
	v_mfma_f32_16x16x32_bf16 v[30:33], v[162:165], v[202:205], v[30:33]
	v_mfma_f32_16x16x32_bf16 v[30:33], v[158:161], v[198:201], v[30:33]
	v_mfma_f32_16x16x32_bf16 v[14:17], v[158:161], v[206:209], v[14:17]
	v_mfma_f32_16x16x32_bf16 v[14:17], v[162:165], v[210:213], v[14:17]
	v_mfma_f32_16x16x32_bf16 v[22:25], v[154:157], v[210:213], v[22:25]
	v_mfma_f32_16x16x32_bf16 v[22:25], v[150:153], v[206:209], v[22:25]
	s_setprio 0
	s_setprio 1
	v_mfma_f32_16x16x32_bf16 v[50:53], v[166:169], v[182:185], v[50:53]
	v_mfma_f32_16x16x32_bf16 v[50:53], v[170:173], v[186:189], v[50:53]
	v_mfma_f32_16x16x32_bf16 v[42:45], v[178:181], v[186:189], v[42:45]
	v_mfma_f32_16x16x32_bf16 v[42:45], v[174:177], v[182:185], v[42:45]
	v_mfma_f32_16x16x32_bf16 v[26:29], v[174:177], v[190:193], v[26:29]
	v_mfma_f32_16x16x32_bf16 v[26:29], v[178:181], v[194:197], v[26:29]
	v_mfma_f32_16x16x32_bf16 v[34:37], v[170:173], v[194:197], v[34:37]
	v_mfma_f32_16x16x32_bf16 v[34:37], v[166:169], v[190:193], v[34:37]
	v_mfma_f32_16x16x32_bf16 v[18:21], v[166:169], v[198:201], v[18:21]
	v_mfma_f32_16x16x32_bf16 v[18:21], v[170:173], v[202:205], v[18:21]
	v_mfma_f32_16x16x32_bf16 v[10:13], v[178:181], v[202:205], v[10:13]
	v_mfma_f32_16x16x32_bf16 v[10:13], v[174:177], v[198:201], v[10:13]
	v_mfma_f32_16x16x32_bf16 v[2:5], v[174:177], v[206:209], v[2:5]
	v_mfma_f32_16x16x32_bf16 v[2:5], v[178:181], v[210:213], v[2:5]
	v_mfma_f32_16x16x32_bf16 v[6:9], v[170:173], v[210:213], v[6:9]
	v_mfma_f32_16x16x32_bf16 v[6:9], v[166:169], v[206:209], v[6:9]
	s_setprio 0
	s_barrier
	s_add_i32 s55, 0, 0x18000
	v_add_u32_e32 v162, s55, v145
	ds_read_b128 v[150:153], v162
	ds_read_b128 v[154:157], v162 offset:1024
	ds_read_b128 v[158:161], v162 offset:2048
	ds_read_b128 v[162:165], v162 offset:3072
	s_add_i32 s56, 0, 0x1c000
	v_add_u32_e32 v178, s56, v145
	ds_read_b128 v[166:169], v178
	ds_read_b128 v[170:173], v178 offset:1024
	s_add_u32 s36, s36, 0x80000
	s_addc_u32 s37, s37, 0
	s_mov_b32 m0, s41
	v_lshl_add_u64 v[220:221], s[36:37], 0, v[130:131]
	global_load_lds_dwordx4 v[220:221], off
	ds_read_b128 v[174:177], v178 offset:2048
	ds_read_b128 v[178:181], v178 offset:3072
	ds_read_b128 v[182:185], v149 offset:32768
	ds_read_b128 v[186:189], v149 offset:33792
	ds_read_b128 v[190:193], v149 offset:34816
	ds_read_b128 v[194:197], v149 offset:35840
	v_lshl_add_u64 v[220:221], s[36:37], 0, v[134:135]
	s_mov_b32 m0, s42
	s_nop 0
	global_load_lds_dwordx4 v[220:221], off
	ds_read_b128 v[198:201], v149 offset:36864
	ds_read_b128 v[202:205], v149 offset:37888
	ds_read_b128 v[206:209], v149 offset:38912
	ds_read_b128 v[210:213], v149 offset:39936
	s_waitcnt vmcnt(8)
	s_waitcnt lgkmcnt(0)
	s_barrier
	s_setprio 1
	s_waitcnt lgkmcnt(0)
	v_mfma_f32_16x16x32_bf16 v[126:129], v[150:153], v[182:185], v[126:129]
	v_mfma_f32_16x16x32_bf16 v[126:129], v[154:157], v[186:189], v[126:129]
	v_mfma_f32_16x16x32_bf16 v[122:125], v[162:165], v[186:189], v[122:125]
	v_mfma_f32_16x16x32_bf16 v[122:125], v[158:161], v[182:185], v[122:125]
	v_mfma_f32_16x16x32_bf16 v[110:113], v[158:161], v[190:193], v[110:113]
	v_mfma_f32_16x16x32_bf16 v[110:113], v[162:165], v[194:197], v[110:113]
	v_mfma_f32_16x16x32_bf16 v[118:121], v[154:157], v[194:197], v[118:121]
	v_mfma_f32_16x16x32_bf16 v[118:121], v[150:153], v[190:193], v[118:121]
	v_mfma_f32_16x16x32_bf16 v[102:105], v[150:153], v[198:201], v[102:105]
	v_mfma_f32_16x16x32_bf16 v[102:105], v[154:157], v[202:205], v[102:105]
	v_mfma_f32_16x16x32_bf16 v[94:97], v[162:165], v[202:205], v[94:97]
	v_mfma_f32_16x16x32_bf16 v[94:97], v[158:161], v[198:201], v[94:97]
	v_mfma_f32_16x16x32_bf16 v[78:81], v[158:161], v[206:209], v[78:81]
	v_mfma_f32_16x16x32_bf16 v[78:81], v[162:165], v[210:213], v[78:81]
	v_mfma_f32_16x16x32_bf16 v[86:89], v[154:157], v[210:213], v[86:89]
	v_mfma_f32_16x16x32_bf16 v[86:89], v[150:153], v[206:209], v[86:89]
	s_setprio 0
	s_setprio 1
	v_mfma_f32_16x16x32_bf16 v[114:117], v[166:169], v[182:185], v[114:117]
	v_mfma_f32_16x16x32_bf16 v[114:117], v[170:173], v[186:189], v[114:117]
	v_mfma_f32_16x16x32_bf16 v[106:109], v[178:181], v[186:189], v[106:109]
	v_mfma_f32_16x16x32_bf16 v[106:109], v[174:177], v[182:185], v[106:109]
	v_mfma_f32_16x16x32_bf16 v[90:93], v[174:177], v[190:193], v[90:93]
	v_mfma_f32_16x16x32_bf16 v[90:93], v[178:181], v[194:197], v[90:93]
	v_mfma_f32_16x16x32_bf16 v[98:101], v[170:173], v[194:197], v[98:101]
	v_mfma_f32_16x16x32_bf16 v[98:101], v[166:169], v[190:193], v[98:101]
	v_mfma_f32_16x16x32_bf16 v[82:85], v[166:169], v[198:201], v[82:85]
	v_mfma_f32_16x16x32_bf16 v[82:85], v[170:173], v[202:205], v[82:85]
	v_mfma_f32_16x16x32_bf16 v[74:77], v[178:181], v[202:205], v[74:77]
	v_mfma_f32_16x16x32_bf16 v[74:77], v[174:177], v[198:201], v[74:77]
	v_mfma_f32_16x16x32_bf16 v[66:69], v[174:177], v[206:209], v[66:69]
	v_mfma_f32_16x16x32_bf16 v[66:69], v[178:181], v[210:213], v[66:69]
	v_mfma_f32_16x16x32_bf16 v[70:73], v[170:173], v[210:213], v[70:73]
	v_mfma_f32_16x16x32_bf16 v[70:73], v[166:169], v[206:209], v[70:73]
	s_setprio 0
	s_barrier
; #define PG8_STAGE(bufoff, gbase, voff) do { _Pragma("unroll") for (int _i = 0; _i < 2; ++_i) \
;         __builtin_amdgcn_global_load_lds((const unsigned*)((const char*)(gbase) + (voff)[_i]), (PG8_LAS unsigned*)(lds + (bufoff) + ldsw + _i * 8192), 16, 0, 0); } while (0)
; #define PG8_LDA(dst, b, h) do { _Pragma("unroll") for (int m = 0; m < 4; ++m) _Pragma("unroll") for (int k = 0; k < 2; ++k) dst[m][k] = *(const PG8_LAS bf16x8*)(lds + PG8_SA(b, h) + aoff + m * 2048 + k * 1024); } while (0)
; #define PG8_MMA(ai, bj, At, Bt) do { __builtin_amdgcn_s_setprio(1); _Pragma("unroll") for (int m = 0; m < 4; ++m) _Pragma("unroll") for (int n = 0; n < 2; ++n) _Pragma("unroll") for (int k = 0; k < 2; ++k) \
;         acc[ai][bj][m][n] = __builtin_amdgcn_mfma_f32_16x16x32_bf16(Bt[n][k], At[m][k], acc[ai][bj][m][n], 0, 0, 0); __builtin_amdgcn_s_setprio(0); } while (0)
; #define PG8_WAIT_V(n) asm volatile("s_waitcnt vmcnt(" #n ")" ::: "memory")
; #define PG8_WAIT_L(n) asm volatile("s_waitcnt lgkmcnt(" #n ")" ::: "memory")
; #define PG8_BAR __builtin_amdgcn_s_barrier()
; #define PG8_SCHED __builtin_amdgcn_sched_barrier(0)
; template <class Epi, class Sched, bool ALIGN_EPI>
; __device__ __forceinline__ void gemm_phase(PG8_LAS unsigned char* lds, const Gemm g, const Sched& S, const Epi& E) {
;     ...
;         for (int t = 0; t < nt; t += 2) {
;     ...
;             PG8_LDA(At, 1, 1); PG8_STAGE(PG8_SB(1, 0), b3, voffB); PG8_STAGE(PG8_SB(1, 1), b3 + hstepB, voffB); PG8_STAGE(PG8_SA(1, 0), a3, voffA);
;             PG8_WAIT_V(8); PG8_WAIT_L(0); PG8_BAR; PG8_MMA(1, 0, At, B0); PG8_MMA(1, 1, At, B1); PG8_BAR; PG8_SCHED;
	ds_read_b128 v[182:185], v149 offset:49152
	ds_read_b128 v[186:189], v149 offset:50176
	s_add_i32 s36, s55, s39
	v_lshl_add_u64 v[142:143], v[142:143], 0, s[8:9]
	s_mov_b32 m0, s36
	s_nop 0
	global_load_lds_dwordx4 v[142:143], off
	ds_read_b128 v[190:193], v149 offset:51200
	ds_read_b128 v[194:197], v149 offset:52224
	s_add_i32 m0, s36, 0x2000
	v_lshl_add_u64 v[142:143], v[214:215], 0, s[8:9]
	global_load_lds_dwordx4 v[142:143], off
	ds_read_b128 v[198:201], v149 offset:53248
	ds_read_b128 v[202:205], v149 offset:54272
	s_add_u32 s34, s34, 0x80080
	s_addc_u32 s35, s35, 0
	s_add_i32 s36, s56, s39
	v_lshl_add_u64 v[142:143], s[34:35], 0, v[132:133]
	s_mov_b32 m0, s36
	s_nop 0
	global_load_lds_dwordx4 v[142:143], off
	ds_read_b128 v[206:209], v149 offset:55296
	ds_read_b128 v[210:213], v149 offset:56320
	v_lshl_add_u64 v[142:143], s[34:35], 0, v[136:137]
	s_add_i32 m0, s36, 0x2000
	s_nop 0
	global_load_lds_dwordx4 v[142:143], off
	v_lshl_add_u64 v[142:143], v[216:217], 0, s[8:9]
	s_mov_b32 m0, s44
	s_nop 0
	global_load_lds_dwordx4 v[142:143], off
	v_lshl_add_u64 v[142:143], v[218:219], 0, s[8:9]
	s_mov_b32 m0, s45
	s_nop 0
	global_load_lds_dwordx4 v[142:143], off
	s_waitcnt vmcnt(8)
	s_waitcnt lgkmcnt(0)
	s_barrier
	s_setprio 1
	s_waitcnt lgkmcnt(0)
	v_mfma_f32_16x16x32_bf16 v[62:65], v[150:153], v[182:185], v[62:65]
	v_mfma_f32_16x16x32_bf16 v[62:65], v[154:157], v[186:189], v[62:65]
	v_mfma_f32_16x16x32_bf16 v[58:61], v[162:165], v[186:189], v[58:61]
	v_mfma_f32_16x16x32_bf16 v[58:61], v[158:161], v[182:185], v[58:61]
	v_mfma_f32_16x16x32_bf16 v[46:49], v[158:161], v[190:193], v[46:49]
	v_mfma_f32_16x16x32_bf16 v[46:49], v[162:165], v[194:197], v[46:49]
	v_mfma_f32_16x16x32_bf16 v[54:57], v[154:157], v[194:197], v[54:57]
	v_mfma_f32_16x16x32_bf16 v[54:57], v[150:153], v[190:193], v[54:57]
	v_mfma_f32_16x16x32_bf16 v[38:41], v[150:153], v[198:201], v[38:41]
	v_mfma_f32_16x16x32_bf16 v[38:41], v[154:157], v[202:205], v[38:41]
	v_mfma_f32_16x16x32_bf16 v[30:33], v[162:165], v[202:205], v[30:33]
	v_mfma_f32_16x16x32_bf16 v[30:33], v[158:161], v[198:201], v[30:33]
	v_mfma_f32_16x16x32_bf16 v[14:17], v[158:161], v[206:209], v[14:17]
	v_mfma_f32_16x16x32_bf16 v[14:17], v[162:165], v[210:213], v[14:17]
	v_mfma_f32_16x16x32_bf16 v[22:25], v[154:157], v[210:213], v[22:25]
	v_mfma_f32_16x16x32_bf16 v[22:25], v[150:153], v[206:209], v[22:25]
	s_setprio 0
	s_setprio 1
	v_mfma_f32_16x16x32_bf16 v[50:53], v[166:169], v[182:185], v[50:53]
	v_mfma_f32_16x16x32_bf16 v[50:53], v[170:173], v[186:189], v[50:53]
	v_mfma_f32_16x16x32_bf16 v[42:45], v[178:181], v[186:189], v[42:45]
	v_mfma_f32_16x16x32_bf16 v[42:45], v[174:177], v[182:185], v[42:45]
	v_mfma_f32_16x16x32_bf16 v[26:29], v[174:177], v[190:193], v[26:29]
	v_mfma_f32_16x16x32_bf16 v[26:29], v[178:181], v[194:197], v[26:29]
	v_mfma_f32_16x16x32_bf16 v[34:37], v[170:173], v[194:197], v[34:37]
	v_mfma_f32_16x16x32_bf16 v[34:37], v[166:169], v[190:193], v[34:37]
	v_mfma_f32_16x16x32_bf16 v[18:21], v[166:169], v[198:201], v[18:21]
	v_mfma_f32_16x16x32_bf16 v[18:21], v[170:173], v[202:205], v[18:21]
	v_mfma_f32_16x16x32_bf16 v[10:13], v[178:181], v[202:205], v[10:13]
	v_mfma_f32_16x16x32_bf16 v[10:13], v[174:177], v[198:201], v[10:13]
	v_mfma_f32_16x16x32_bf16 v[2:5], v[174:177], v[206:209], v[2:5]
	v_mfma_f32_16x16x32_bf16 v[2:5], v[178:181], v[210:213], v[2:5]
	v_mfma_f32_16x16x32_bf16 v[6:9], v[170:173], v[210:213], v[6:9]
	v_mfma_f32_16x16x32_bf16 v[6:9], v[166:169], v[206:209], v[6:9]
	s_setprio 0
	s_barrier
	s_add_i32 s54, s54, 2
	s_add_u32 s30, s30, 0x100
	s_addc_u32 s31, s31, 0
	s_add_u32 s21, s21, 0x100
	s_addc_u32 s23, s23, 0
	s_cmp_gt_u32 s54, 29
	s_cbranch_scc0 .LBB0_431
	s_and_b64 vcc, exec, s[10:11]
	s_cbranch_vccz .LBB0_434
	s_barrier

; #define PG8_STAGE(bufoff, gbase, voff) do { _Pragma("unroll") for (int _i = 0; _i < 2; ++_i) \
;         __builtin_amdgcn_global_load_lds((const unsigned*)((const char*)(gbase) + (voff)[_i]), (PG8_LAS unsigned*)(lds + (bufoff) + ldsw + _i * 8192), 16, 0, 0); } while (0)
; #define PG8_LDA(dst, b, h) do { _Pragma("unroll") for (int m = 0; m < 4; ++m) _Pragma("unroll") for (int k = 0; k < 2; ++k) dst[m][k] = *(const PG8_LAS bf16x8*)(lds + PG8_SA(b, h) + aoff + m * 2048 + k * 1024); } while (0)
; #define PG8_LDB(dst, b, h) do { _Pragma("unroll") for (int n = 0; n < 2; ++n) _Pragma("unroll") for (int k = 0; k < 2; ++k) dst[n][k] = *(const PG8_LAS bf16x8*)(lds + PG8_SB(b, h) + boff + n * 2048 + k * 1024); } while (0)
; #define PG8_MMA(ai, bj, At, Bt) do { __builtin_amdgcn_s_setprio(1); _Pragma("unroll") for (int m = 0; m < 4; ++m) _Pragma("unroll") for (int n = 0; n < 2; ++n) _Pragma("unroll") for (int k = 0; k < 2; ++k) \
;         acc[ai][bj][m][n] = __builtin_amdgcn_mfma_f32_16x16x32_bf16(Bt[n][k], At[m][k], acc[ai][bj][m][n], 0, 0, 0); __builtin_amdgcn_s_setprio(0); } while (0)
; #define PG8_WAIT_V(n) asm volatile("s_waitcnt vmcnt(" #n ")" ::: "memory")
; #define PG8_WAIT_L(n) asm volatile("s_waitcnt lgkmcnt(" #n ")" ::: "memory")
; #define PG8_BAR __builtin_amdgcn_s_barrier()
; #define PG8_SCHED __builtin_amdgcn_sched_barrier(0)
; template <class Epi, class Sched, bool ALIGN_EPI>
; __device__ __forceinline__ void gemm_phase(PG8_LAS unsigned char* lds, const Gemm g, const Sched& S, const Epi& E) {
;     ...
;             const char* a1 = cA + (size_t)(t + 1) * kstepA;
;             const char* a2 = last ? nA : cA + (size_t)(t + 2) * kstepA; const char* b2 = last ? nB : cB + (size_t)(t + 2) * kstep;
;             const char* a3 = a2 + kstepA; const char* b3 = b2 + kstep;
;             PG8_LDB(B0, 0, 0); PG8_LDB(B1, 0, 1); PG8_SCHED; PG8_LDA(At, 0, 0); PG8_STAGE(PG8_SA(1, 1), a1 + hstepA, voffA);
;             PG8_WAIT_V(8); PG8_WAIT_L(0); PG8_BAR; PG8_MMA(0, 0, At, B0); PG8_MMA(0, 1, At, B1); PG8_BAR; PG8_SCHED;
;             PG8_LDA(At, 0, 1); PG8_STAGE(PG8_SB(0, 0), b2, voffB); PG8_STAGE(PG8_SB(0, 1), b2 + hstepB, voffB); PG8_STAGE(PG8_SA(0, 0), a2, voffA);
;             PG8_WAIT_V(8); PG8_WAIT_L(0); PG8_BAR; PG8_MMA(1, 0, At, B0); PG8_MMA(1, 1, At, B1); PG8_BAR; PG8_SCHED;
.LBB0_778:
	ds_read_b128 v[114:117], v178
	ds_read_b128 v[118:121], v178 offset:1024
	ds_read_b128 v[156:159], v178 offset:2048
	ds_read_b128 v[160:163], v178 offset:3072
	ds_read_b128 v[164:167], v179
	ds_read_b128 v[168:171], v179 offset:1024
	s_add_u32 s36, s34, 0x400000
	s_addc_u32 s37, s35, 0
	s_cmp_eq_u32 s21, 12
	s_cselect_b32 s42, s24, s36
	s_cselect_b32 s43, s25, s37
	s_cselect_b32 s40, s26, s4
	s_cselect_b32 s41, s27, s5
	s_add_u32 s38, s42, 0x200000
	s_addc_u32 s39, s43, 0
	v_lshl_add_u64 v[222:223], s[34:35], 0, v[148:149]
	s_add_i32 m0, s31, 0xc000
	s_nop 0
	global_load_lds_dwordx4 v[222:223], off
	ds_read_b128 v[182:185], v179 offset:2048
	ds_read_b128 v[186:189], v179 offset:3072
	ds_read_b128 v[190:193], v180
	ds_read_b128 v[194:197], v180 offset:1024
	ds_read_b128 v[198:201], v180 offset:2048
	ds_read_b128 v[202:205], v180 offset:3072
	v_lshl_add_u64 v[222:223], s[34:35], 0, v[150:151]
	s_add_i32 m0, s31, 0xe000
	s_nop 0
	global_load_lds_dwordx4 v[222:223], off
	ds_read_b128 v[206:209], v180 offset:4096
	ds_read_b128 v[210:213], v180 offset:5120
	ds_read_b128 v[214:217], v180 offset:6144
	ds_read_b128 v[218:221], v180 offset:7168
	s_waitcnt vmcnt(8)
	s_waitcnt lgkmcnt(0)
	s_barrier
	s_setprio 1
	s_waitcnt lgkmcnt(0)
	v_mfma_f32_16x16x32_bf16 v[134:137], v[114:117], v[190:193], v[134:137]
	v_mfma_f32_16x16x32_bf16 v[134:137], v[118:121], v[194:197], v[134:137]
	v_mfma_f32_16x16x32_bf16 v[130:133], v[160:163], v[194:197], v[130:133]
	v_mfma_f32_16x16x32_bf16 v[130:133], v[156:159], v[190:193], v[130:133]
	v_mfma_f32_16x16x32_bf16 v[122:125], v[156:159], v[198:201], v[122:125]
	v_mfma_f32_16x16x32_bf16 v[122:125], v[160:163], v[202:205], v[122:125]
	v_mfma_f32_16x16x32_bf16 v[126:129], v[118:121], v[202:205], v[126:129]
	v_mfma_f32_16x16x32_bf16 v[126:129], v[114:117], v[198:201], v[126:129]
	v_mfma_f32_16x16x32_bf16 v[110:113], v[114:117], v[206:209], v[110:113]
	v_mfma_f32_16x16x32_bf16 v[110:113], v[118:121], v[210:213], v[110:113]
	v_mfma_f32_16x16x32_bf16 v[106:109], v[160:163], v[210:213], v[106:109]
	v_mfma_f32_16x16x32_bf16 v[106:109], v[156:159], v[206:209], v[106:109]
	v_mfma_f32_16x16x32_bf16 v[98:101], v[156:159], v[214:217], v[98:101]
	v_mfma_f32_16x16x32_bf16 v[98:101], v[160:163], v[218:221], v[98:101]
	v_mfma_f32_16x16x32_bf16 v[102:105], v[118:121], v[218:221], v[102:105]
	v_mfma_f32_16x16x32_bf16 v[102:105], v[114:117], v[214:217], v[102:105]
	s_setprio 0
	s_setprio 1
	v_mfma_f32_16x16x32_bf16 v[62:65], v[164:167], v[190:193], v[62:65]
	v_mfma_f32_16x16x32_bf16 v[62:65], v[168:171], v[194:197], v[62:65]
	v_mfma_f32_16x16x32_bf16 v[58:61], v[186:189], v[194:197], v[58:61]
	v_mfma_f32_16x16x32_bf16 v[58:61], v[182:185], v[190:193], v[58:61]
	v_mfma_f32_16x16x32_bf16 v[50:53], v[182:185], v[198:201], v[50:53]
	v_mfma_f32_16x16x32_bf16 v[50:53], v[186:189], v[202:205], v[50:53]
	v_mfma_f32_16x16x32_bf16 v[54:57], v[168:171], v[202:205], v[54:57]
	v_mfma_f32_16x16x32_bf16 v[54:57], v[164:167], v[198:201], v[54:57]
	v_mfma_f32_16x16x32_bf16 v[46:49], v[164:167], v[206:209], v[46:49]
	v_mfma_f32_16x16x32_bf16 v[46:49], v[168:171], v[210:213], v[46:49]
	v_mfma_f32_16x16x32_bf16 v[42:45], v[186:189], v[210:213], v[42:45]
	v_mfma_f32_16x16x32_bf16 v[42:45], v[182:185], v[206:209], v[42:45]
	v_mfma_f32_16x16x32_bf16 v[34:37], v[182:185], v[214:217], v[34:37]
	v_mfma_f32_16x16x32_bf16 v[34:37], v[186:189], v[218:221], v[34:37]
	v_mfma_f32_16x16x32_bf16 v[38:41], v[168:171], v[218:221], v[38:41]
	v_mfma_f32_16x16x32_bf16 v[38:41], v[164:167], v[214:217], v[38:41]
	s_setprio 0
	s_barrier
	ds_read_b128 v[190:193], v180 offset:16384
	ds_read_b128 v[194:197], v180 offset:17408
	s_add_i32 s2, s52, s3
	v_lshl_add_u64 v[222:223], s[40:41], 0, v[140:141]
	s_mov_b32 m0, s2
	s_nop 0
	global_load_lds_dwordx4 v[222:223], off
	ds_read_b128 v[198:201], v180 offset:18432
	ds_read_b128 v[202:205], v180 offset:19456
	s_add_i32 m0, s2, 0x2000
	v_lshl_add_u64 v[224:225], s[40:41], 0, v[144:145]
	global_load_lds_dwordx4 v[224:225], off
	ds_read_b128 v[206:209], v180 offset:20480
	ds_read_b128 v[210:213], v180 offset:21504
	s_add_u32 s34, s40, 0x40000
	s_addc_u32 s35, s41, 0
	s_add_i32 s2, s53, s3
	v_lshl_add_u64 v[226:227], s[34:35], 0, v[140:141]
	s_mov_b32 m0, s2
	s_nop 0
	global_load_lds_dwordx4 v[226:227], off
	ds_read_b128 v[214:217], v180 offset:22528
	ds_read_b128 v[218:221], v180 offset:23552
	v_lshl_add_u64 v[226:227], s[34:35], 0, v[144:145]
	s_add_i32 m0, s2, 0x2000
	s_nop 0
	global_load_lds_dwordx4 v[226:227], off
	v_lshl_add_u64 v[226:227], s[42:43], 0, v[138:139]
	s_mov_b32 m0, s31
	s_nop 0
	global_load_lds_dwordx4 v[226:227], off
	v_lshl_add_u64 v[226:227], s[42:43], 0, v[142:143]
	s_mov_b32 m0, s44
	s_nop 0
	global_load_lds_dwordx4 v[226:227], off
	s_waitcnt vmcnt(8)
	s_waitcnt lgkmcnt(0)
	s_barrier
; #define PG8_STAGE(bufoff, gbase, voff) do { _Pragma("unroll") for (int _i = 0; _i < 2; ++_i) \
;         __builtin_amdgcn_global_load_lds((const unsigned*)((const char*)(gbase) + (voff)[_i]), (PG8_LAS unsigned*)(lds + (bufoff) + ldsw + _i * 8192), 16, 0, 0); } while (0)
; #define PG8_LDA(dst, b, h) do { _Pragma("unroll") for (int m = 0; m < 4; ++m) _Pragma("unroll") for (int k = 0; k < 2; ++k) dst[m][k] = *(const PG8_LAS bf16x8*)(lds + PG8_SA(b, h) + aoff + m * 2048 + k * 1024); } while (0)
; #define PG8_LDB(dst, b, h) do { _Pragma("unroll") for (int n = 0; n < 2; ++n) _Pragma("unroll") for (int k = 0; k < 2; ++k) dst[n][k] = *(const PG8_LAS bf16x8*)(lds + PG8_SB(b, h) + boff + n * 2048 + k * 1024); } while (0)
; #define PG8_MMA(ai, bj, At, Bt) do { __builtin_amdgcn_s_setprio(1); _Pragma("unroll") for (int m = 0; m < 4; ++m) _Pragma("unroll") for (int n = 0; n < 2; ++n) _Pragma("unroll") for (int k = 0; k < 2; ++k) \
;         acc[ai][bj][m][n] = __builtin_amdgcn_mfma_f32_16x16x32_bf16(Bt[n][k], At[m][k], acc[ai][bj][m][n], 0, 0, 0); __builtin_amdgcn_s_setprio(0); } while (0)
; #define PG8_WAIT_V(n) asm volatile("s_waitcnt vmcnt(" #n ")" ::: "memory")
; #define PG8_WAIT_L(n) asm volatile("s_waitcnt lgkmcnt(" #n ")" ::: "memory")
; #define PG8_BAR __builtin_amdgcn_s_barrier()
; template <class Epi, class Sched, bool ALIGN_EPI>
; __device__ __forceinline__ void gemm_phase(PG8_LAS unsigned char* lds, const Gemm g, const Sched& S, const Epi& E) {
;     ...
;             PG8_WAIT_V(8); PG8_WAIT_L(0); PG8_BAR; PG8_MMA(0, 0, At, B0); PG8_MMA(0, 1, At, B1); PG8_BAR; PG8_SCHED;
;             PG8_LDA(At, 0, 1); PG8_STAGE(PG8_SB(0, 0), b2, voffB); PG8_STAGE(PG8_SB(0, 1), b2 + hstepB, voffB); PG8_STAGE(PG8_SA(0, 0), a2, voffA);
;             PG8_WAIT_V(8); PG8_WAIT_L(0); PG8_BAR; PG8_MMA(1, 0, At, B0); PG8_MMA(1, 1, At, B1); PG8_BAR; PG8_SCHED;
;             PG8_LDB(B0, 1, 0); PG8_LDB(B1, 1, 1); PG8_SCHED; PG8_LDA(At, 1, 0); PG8_STAGE(PG8_SA(0, 1), a2 + hstepA, voffA);
;             PG8_WAIT_V(8); PG8_WAIT_L(0); PG8_BAR; PG8_MMA(0, 0, At, B0); PG8_MMA(0, 1, At, B1); PG8_BAR; PG8_SCHED;
;             PG8_LDA(At, 1, 1); PG8_STAGE(PG8_SB(1, 0), b3, voffB); PG8_STAGE(PG8_SB(1, 1), b3 + hstepB, voffB); PG8_STAGE(PG8_SA(1, 0), a3, voffA);
;             PG8_WAIT_V(8); PG8_WAIT_L(0); PG8_BAR; PG8_MMA(1, 0, At, B0); PG8_MMA(1, 1, At, B1); PG8_BAR; PG8_SCHED;
	s_setprio 1
	s_waitcnt lgkmcnt(0)
	v_mfma_f32_16x16x32_bf16 v[94:97], v[114:117], v[190:193], v[94:97]
	v_mfma_f32_16x16x32_bf16 v[94:97], v[118:121], v[194:197], v[94:97]
	v_mfma_f32_16x16x32_bf16 v[90:93], v[160:163], v[194:197], v[90:93]
	v_mfma_f32_16x16x32_bf16 v[90:93], v[156:159], v[190:193], v[90:93]
	v_mfma_f32_16x16x32_bf16 v[82:85], v[156:159], v[198:201], v[82:85]
	v_mfma_f32_16x16x32_bf16 v[82:85], v[160:163], v[202:205], v[82:85]
	v_mfma_f32_16x16x32_bf16 v[86:89], v[118:121], v[202:205], v[86:89]
	v_mfma_f32_16x16x32_bf16 v[86:89], v[114:117], v[198:201], v[86:89]
	v_mfma_f32_16x16x32_bf16 v[78:81], v[114:117], v[206:209], v[78:81]
	v_mfma_f32_16x16x32_bf16 v[78:81], v[118:121], v[210:213], v[78:81]
	v_mfma_f32_16x16x32_bf16 v[74:77], v[160:163], v[210:213], v[74:77]
	v_mfma_f32_16x16x32_bf16 v[74:77], v[156:159], v[206:209], v[74:77]
	v_mfma_f32_16x16x32_bf16 v[66:69], v[156:159], v[214:217], v[66:69]
	v_mfma_f32_16x16x32_bf16 v[66:69], v[160:163], v[218:221], v[66:69]
	v_mfma_f32_16x16x32_bf16 v[70:73], v[118:121], v[218:221], v[70:73]
	v_mfma_f32_16x16x32_bf16 v[70:73], v[114:117], v[214:217], v[70:73]
	s_setprio 0
	s_setprio 1
	v_mfma_f32_16x16x32_bf16 v[30:33], v[164:167], v[190:193], v[30:33]
	v_mfma_f32_16x16x32_bf16 v[30:33], v[168:171], v[194:197], v[30:33]
	v_mfma_f32_16x16x32_bf16 v[26:29], v[186:189], v[194:197], v[26:29]
	v_mfma_f32_16x16x32_bf16 v[26:29], v[182:185], v[190:193], v[26:29]
	v_mfma_f32_16x16x32_bf16 v[18:21], v[182:185], v[198:201], v[18:21]
	v_mfma_f32_16x16x32_bf16 v[18:21], v[186:189], v[202:205], v[18:21]
	v_mfma_f32_16x16x32_bf16 v[22:25], v[168:171], v[202:205], v[22:25]
	v_mfma_f32_16x16x32_bf16 v[22:25], v[164:167], v[198:201], v[22:25]
	v_mfma_f32_16x16x32_bf16 v[14:17], v[164:167], v[206:209], v[14:17]
	v_mfma_f32_16x16x32_bf16 v[14:17], v[168:171], v[210:213], v[14:17]
	v_mfma_f32_16x16x32_bf16 v[10:13], v[186:189], v[210:213], v[10:13]
	v_mfma_f32_16x16x32_bf16 v[10:13], v[182:185], v[206:209], v[10:13]
	v_mfma_f32_16x16x32_bf16 v[2:5], v[182:185], v[214:217], v[2:5]
	v_mfma_f32_16x16x32_bf16 v[2:5], v[186:189], v[218:221], v[2:5]
	v_mfma_f32_16x16x32_bf16 v[6:9], v[168:171], v[218:221], v[6:9]
	v_mfma_f32_16x16x32_bf16 v[6:9], v[164:167], v[214:217], v[6:9]
	s_setprio 0
	s_barrier
	s_add_i32 s2, 0, 0x18000
	v_add_u32_e32 v160, s2, v175
	ds_read_b128 v[114:117], v160
	ds_read_b128 v[118:121], v160 offset:1024
	ds_read_b128 v[156:159], v160 offset:2048
	ds_read_b128 v[160:163], v160 offset:3072
	s_add_i32 s23, 0, 0x1c000
	v_add_u32_e32 v181, s23, v175
	ds_read_b128 v[164:167], v181
	ds_read_b128 v[168:171], v181 offset:1024
	s_add_u32 s34, s42, 0x1000
	s_addc_u32 s35, s43, 0
	s_mov_b32 m0, s45
	v_lshl_add_u64 v[226:227], s[34:35], 0, v[138:139]
	global_load_lds_dwordx4 v[226:227], off
	ds_read_b128 v[182:185], v181 offset:2048
	ds_read_b128 v[186:189], v181 offset:3072
	ds_read_b128 v[190:193], v180 offset:32768
	ds_read_b128 v[194:197], v180 offset:33792
	ds_read_b128 v[198:201], v180 offset:34816
	ds_read_b128 v[202:205], v180 offset:35840
	v_lshl_add_u64 v[226:227], s[34:35], 0, v[142:143]
	s_mov_b32 m0, s46
	s_nop 0
	global_load_lds_dwordx4 v[226:227], off
	ds_read_b128 v[206:209], v180 offset:36864
	ds_read_b128 v[210:213], v180 offset:37888
	ds_read_b128 v[214:217], v180 offset:38912
	ds_read_b128 v[218:221], v180 offset:39936
	s_waitcnt vmcnt(8)
	s_waitcnt lgkmcnt(0)
	s_barrier
	s_setprio 1
	s_waitcnt lgkmcnt(0)
	v_mfma_f32_16x16x32_bf16 v[134:137], v[114:117], v[190:193], v[134:137]
	v_mfma_f32_16x16x32_bf16 v[134:137], v[118:121], v[194:197], v[134:137]
	v_mfma_f32_16x16x32_bf16 v[130:133], v[160:163], v[194:197], v[130:133]
	v_mfma_f32_16x16x32_bf16 v[130:133], v[156:159], v[190:193], v[130:133]
	v_mfma_f32_16x16x32_bf16 v[122:125], v[156:159], v[198:201], v[122:125]
	v_mfma_f32_16x16x32_bf16 v[122:125], v[160:163], v[202:205], v[122:125]
	v_mfma_f32_16x16x32_bf16 v[126:129], v[118:121], v[202:205], v[126:129]
	v_mfma_f32_16x16x32_bf16 v[126:129], v[114:117], v[198:201], v[126:129]
	v_mfma_f32_16x16x32_bf16 v[110:113], v[114:117], v[206:209], v[110:113]
	v_mfma_f32_16x16x32_bf16 v[110:113], v[118:121], v[210:213], v[110:113]
	v_mfma_f32_16x16x32_bf16 v[106:109], v[160:163], v[210:213], v[106:109]
	v_mfma_f32_16x16x32_bf16 v[106:109], v[156:159], v[206:209], v[106:109]
	v_mfma_f32_16x16x32_bf16 v[98:101], v[156:159], v[214:217], v[98:101]
	v_mfma_f32_16x16x32_bf16 v[98:101], v[160:163], v[218:221], v[98:101]
	v_mfma_f32_16x16x32_bf16 v[102:105], v[118:121], v[218:221], v[102:105]
	v_mfma_f32_16x16x32_bf16 v[102:105], v[114:117], v[214:217], v[102:105]
	s_setprio 0
	s_setprio 1
	v_mfma_f32_16x16x32_bf16 v[62:65], v[164:167], v[190:193], v[62:65]
	v_mfma_f32_16x16x32_bf16 v[62:65], v[168:171], v[194:197], v[62:65]
	v_mfma_f32_16x16x32_bf16 v[58:61], v[186:189], v[194:197], v[58:61]
	v_mfma_f32_16x16x32_bf16 v[58:61], v[182:185], v[190:193], v[58:61]
	v_mfma_f32_16x16x32_bf16 v[50:53], v[182:185], v[198:201], v[50:53]
	v_mfma_f32_16x16x32_bf16 v[50:53], v[186:189], v[202:205], v[50:53]
	v_mfma_f32_16x16x32_bf16 v[54:57], v[168:171], v[202:205], v[54:57]
	v_mfma_f32_16x16x32_bf16 v[54:57], v[164:167], v[198:201], v[54:57]
	v_mfma_f32_16x16x32_bf16 v[46:49], v[164:167], v[206:209], v[46:49]
	v_mfma_f32_16x16x32_bf16 v[46:49], v[168:171], v[210:213], v[46:49]
	v_mfma_f32_16x16x32_bf16 v[42:45], v[186:189], v[210:213], v[42:45]
	v_mfma_f32_16x16x32_bf16 v[42:45], v[182:185], v[206:209], v[42:45]
	v_mfma_f32_16x16x32_bf16 v[34:37], v[182:185], v[214:217], v[34:37]
	v_mfma_f32_16x16x32_bf16 v[34:37], v[186:189], v[218:221], v[34:37]
	v_mfma_f32_16x16x32_bf16 v[38:41], v[168:171], v[218:221], v[38:41]
	v_mfma_f32_16x16x32_bf16 v[38:41], v[164:167], v[214:217], v[38:41]
	s_setprio 0
	s_barrier
; #define PG8_STAGE(bufoff, gbase, voff) do { _Pragma("unroll") for (int _i = 0; _i < 2; ++_i) \
;         __builtin_amdgcn_global_load_lds((const unsigned*)((const char*)(gbase) + (voff)[_i]), (PG8_LAS unsigned*)(lds + (bufoff) + ldsw + _i * 8192), 16, 0, 0); } while (0)
; #define PG8_LDA(dst, b, h) do { _Pragma("unroll") for (int m = 0; m < 4; ++m) _Pragma("unroll") for (int k = 0; k < 2; ++k) dst[m][k] = *(const PG8_LAS bf16x8*)(lds + PG8_SA(b, h) + aoff + m * 2048 + k * 1024); } while (0)
; #define PG8_MMA(ai, bj, At, Bt) do { __builtin_amdgcn_s_setprio(1); _Pragma("unroll") for (int m = 0; m < 4; ++m) _Pragma("unroll") for (int n = 0; n < 2; ++n) _Pragma("unroll") for (int k = 0; k < 2; ++k) \
;         acc[ai][bj][m][n] = __builtin_amdgcn_mfma_f32_16x16x32_bf16(Bt[n][k], At[m][k], acc[ai][bj][m][n], 0, 0, 0); __builtin_amdgcn_s_setprio(0); } while (0)
; #define PG8_WAIT_V(n) asm volatile("s_waitcnt vmcnt(" #n ")" ::: "memory")
; #define PG8_WAIT_L(n) asm volatile("s_waitcnt lgkmcnt(" #n ")" ::: "memory")
; #define PG8_BAR __builtin_amdgcn_s_barrier()
; #define PG8_SCHED __builtin_amdgcn_sched_barrier(0)
; template <class Epi, class Sched, bool ALIGN_EPI>
; __device__ __forceinline__ void gemm_phase(PG8_LAS unsigned char* lds, const Gemm g, const Sched& S, const Epi& E) {
;     ...
;         for (int t = 0; t < nt; t += 2) {
;     ...
;             PG8_LDA(At, 1, 1); PG8_STAGE(PG8_SB(1, 0), b3, voffB); PG8_STAGE(PG8_SB(1, 1), b3 + hstepB, voffB); PG8_STAGE(PG8_SA(1, 0), a3, voffA);
;             PG8_WAIT_V(8); PG8_WAIT_L(0); PG8_BAR; PG8_MMA(1, 0, At, B0); PG8_MMA(1, 1, At, B1); PG8_BAR; PG8_SCHED;
	ds_read_b128 v[190:193], v180 offset:49152
	ds_read_b128 v[194:197], v180 offset:50176
	s_add_i32 s2, s2, s3
	v_lshl_add_u64 v[222:223], v[222:223], 0, s[16:17]
	s_mov_b32 m0, s2
	s_nop 0
	global_load_lds_dwordx4 v[222:223], off
	ds_read_b128 v[198:201], v180 offset:51200
	ds_read_b128 v[202:205], v180 offset:52224
	s_add_i32 m0, s2, 0x2000
	v_lshl_add_u64 v[222:223], v[224:225], 0, s[16:17]
	global_load_lds_dwordx4 v[222:223], off
	ds_read_b128 v[206:209], v180 offset:53248
	ds_read_b128 v[210:213], v180 offset:54272
	s_add_u32 s34, s40, 0x40080
	s_addc_u32 s35, s41, 0
	s_add_i32 s2, s23, s3
	v_lshl_add_u64 v[222:223], s[34:35], 0, v[140:141]
	s_mov_b32 m0, s2
	s_nop 0
	global_load_lds_dwordx4 v[222:223], off
	ds_read_b128 v[214:217], v180 offset:55296
	ds_read_b128 v[218:221], v180 offset:56320
	v_lshl_add_u64 v[222:223], s[34:35], 0, v[144:145]
	s_add_i32 m0, s2, 0x2000
	s_nop 0
	global_load_lds_dwordx4 v[222:223], off
	v_lshl_add_u64 v[222:223], s[38:39], 0, v[138:139]
	s_mov_b32 m0, s48
	s_nop 0
	global_load_lds_dwordx4 v[222:223], off
	v_lshl_add_u64 v[222:223], s[38:39], 0, v[142:143]
	s_mov_b32 m0, s49
	s_nop 0
	global_load_lds_dwordx4 v[222:223], off
	s_waitcnt vmcnt(8)
	s_waitcnt lgkmcnt(0)
	s_barrier
	s_setprio 1
	s_waitcnt lgkmcnt(0)
	v_mfma_f32_16x16x32_bf16 v[94:97], v[114:117], v[190:193], v[94:97]
	v_mfma_f32_16x16x32_bf16 v[94:97], v[118:121], v[194:197], v[94:97]
	v_mfma_f32_16x16x32_bf16 v[90:93], v[160:163], v[194:197], v[90:93]
	v_mfma_f32_16x16x32_bf16 v[90:93], v[156:159], v[190:193], v[90:93]
	v_mfma_f32_16x16x32_bf16 v[82:85], v[156:159], v[198:201], v[82:85]
	v_mfma_f32_16x16x32_bf16 v[82:85], v[160:163], v[202:205], v[82:85]
	v_mfma_f32_16x16x32_bf16 v[86:89], v[118:121], v[202:205], v[86:89]
	v_mfma_f32_16x16x32_bf16 v[86:89], v[114:117], v[198:201], v[86:89]
	v_mfma_f32_16x16x32_bf16 v[78:81], v[114:117], v[206:209], v[78:81]
	v_mfma_f32_16x16x32_bf16 v[78:81], v[118:121], v[210:213], v[78:81]
	v_mfma_f32_16x16x32_bf16 v[74:77], v[160:163], v[210:213], v[74:77]
	v_mfma_f32_16x16x32_bf16 v[74:77], v[156:159], v[206:209], v[74:77]
	v_mfma_f32_16x16x32_bf16 v[66:69], v[156:159], v[214:217], v[66:69]
	v_mfma_f32_16x16x32_bf16 v[66:69], v[160:163], v[218:221], v[66:69]
	v_mfma_f32_16x16x32_bf16 v[70:73], v[118:121], v[218:221], v[70:73]
	v_mfma_f32_16x16x32_bf16 v[70:73], v[114:117], v[214:217], v[70:73]
	s_setprio 0
	s_setprio 1
	v_mfma_f32_16x16x32_bf16 v[30:33], v[164:167], v[190:193], v[30:33]
	v_mfma_f32_16x16x32_bf16 v[30:33], v[168:171], v[194:197], v[30:33]
	v_mfma_f32_16x16x32_bf16 v[26:29], v[186:189], v[194:197], v[26:29]
	v_mfma_f32_16x16x32_bf16 v[26:29], v[182:185], v[190:193], v[26:29]
	v_mfma_f32_16x16x32_bf16 v[18:21], v[182:185], v[198:201], v[18:21]
	v_mfma_f32_16x16x32_bf16 v[18:21], v[186:189], v[202:205], v[18:21]
	v_mfma_f32_16x16x32_bf16 v[22:25], v[168:171], v[202:205], v[22:25]
	v_mfma_f32_16x16x32_bf16 v[22:25], v[164:167], v[198:201], v[22:25]
	v_mfma_f32_16x16x32_bf16 v[14:17], v[164:167], v[206:209], v[14:17]
	v_mfma_f32_16x16x32_bf16 v[14:17], v[168:171], v[210:213], v[14:17]
	v_mfma_f32_16x16x32_bf16 v[10:13], v[186:189], v[210:213], v[10:13]
	v_mfma_f32_16x16x32_bf16 v[10:13], v[182:185], v[206:209], v[10:13]
	v_mfma_f32_16x16x32_bf16 v[2:5], v[182:185], v[214:217], v[2:5]
	v_mfma_f32_16x16x32_bf16 v[2:5], v[186:189], v[218:221], v[2:5]
	v_mfma_f32_16x16x32_bf16 v[6:9], v[168:171], v[218:221], v[6:9]
	v_mfma_f32_16x16x32_bf16 v[6:9], v[164:167], v[214:217], v[6:9]
	s_setprio 0
	s_barrier
	s_add_i32 s21, s21, 2
	s_add_u32 s4, s4, 0x100
	s_addc_u32 s5, s5, 0
	s_cmp_gt_u32 s21, 13
	s_mov_b64 s[34:35], s[36:37]
	s_cbranch_scc0 .LBB0_778
	s_and_b64 vcc, exec, s[18:19]
	s_cbranch_vccz .LBB0_781
	s_barrier

; #define PG8_STAGE(bufoff, gbase, voff) do { _Pragma("unroll") for (int _i = 0; _i < 2; ++_i) \
;         __builtin_amdgcn_global_load_lds((const unsigned*)((const char*)(gbase) + (voff)[_i]), (PG8_LAS unsigned*)(lds + (bufoff) + ldsw + _i * 8192), 16, 0, 0); } while (0)
; #define PG8_LDA(dst, b, h) do { _Pragma("unroll") for (int m = 0; m < 4; ++m) _Pragma("unroll") for (int k = 0; k < 2; ++k) dst[m][k] = *(const PG8_LAS bf16x8*)(lds + PG8_SA(b, h) + aoff + m * 2048 + k * 1024); } while (0)
; #define PG8_LDB(dst, b, h) do { _Pragma("unroll") for (int n = 0; n < 2; ++n) _Pragma("unroll") for (int k = 0; k < 2; ++k) dst[n][k] = *(const PG8_LAS bf16x8*)(lds + PG8_SB(b, h) + boff + n * 2048 + k * 1024); } while (0)
; #define PG8_MMA(ai, bj, At, Bt) do { __builtin_amdgcn_s_setprio(1); _Pragma("unroll") for (int m = 0; m < 4; ++m) _Pragma("unroll") for (int n = 0; n < 2; ++n) _Pragma("unroll") for (int k = 0; k < 2; ++k) \
;         acc[ai][bj][m][n] = __builtin_amdgcn_mfma_f32_16x16x32_bf16(Bt[n][k], At[m][k], acc[ai][bj][m][n], 0, 0, 0); __builtin_amdgcn_s_setprio(0); } while (0)
; #define PG8_WAIT_V(n) asm volatile("s_waitcnt vmcnt(" #n ")" ::: "memory")
; #define PG8_WAIT_L(n) asm volatile("s_waitcnt lgkmcnt(" #n ")" ::: "memory")
; #define PG8_BAR __builtin_amdgcn_s_barrier()
; #define PG8_SCHED __builtin_amdgcn_sched_barrier(0)
; template <class Epi, class Sched, bool ALIGN_EPI>
; __device__ __forceinline__ void gemm_phase(PG8_LAS unsigned char* lds, const Gemm g, const Sched& S, const Epi& E) {
;     ...
;             const char* a1 = cA + (size_t)(t + 1) * kstepA;
;             const char* a2 = last ? nA : cA + (size_t)(t + 2) * kstepA; const char* b2 = last ? nB : cB + (size_t)(t + 2) * kstep;
;             const char* a3 = a2 + kstepA; const char* b3 = b2 + kstep;
;             PG8_LDB(B0, 0, 0); PG8_LDB(B1, 0, 1); PG8_SCHED; PG8_LDA(At, 0, 0); PG8_STAGE(PG8_SA(1, 1), a1 + hstepA, voffA);
;             PG8_WAIT_V(8); PG8_WAIT_L(0); PG8_BAR; PG8_MMA(0, 0, At, B0); PG8_MMA(0, 1, At, B1); PG8_BAR; PG8_SCHED;
;             PG8_LDA(At, 0, 1); PG8_STAGE(PG8_SB(0, 0), b2, voffB); PG8_STAGE(PG8_SB(0, 1), b2 + hstepB, voffB); PG8_STAGE(PG8_SA(0, 0), a2, voffA);
;             PG8_WAIT_V(8); PG8_WAIT_L(0); PG8_BAR; PG8_MMA(1, 0, At, B0); PG8_MMA(1, 1, At, B1); PG8_BAR; PG8_SCHED;
.LBB0_839:
	v_add_u32_e32 v3, s55, v155
	ds_read_b128 v[160:163], v3
	ds_read_b128 v[164:167], v3 offset:1024
	ds_read_b128 v[168:171], v3 offset:2048
	ds_read_b128 v[174:177], v3 offset:3072
	v_add_u32_e32 v3, s56, v155
	ds_read_b128 v[178:181], v3
	ds_read_b128 v[182:185], v3 offset:1024
	s_add_u32 s2, s38, s40
	s_addc_u32 s42, s39, s41
	s_add_u32 s2, s2, 0x100
	s_addc_u32 s42, s42, 0
	s_add_u32 s63, s27, s40
	s_addc_u32 s43, s29, s41
	s_cmpk_eq_i32 s40, 0xf00
	s_cselect_b32 s45, s31, s42
	s_cselect_b32 s44, s30, s2
	s_cselect_b32 s43, s35, s43
	s_cselect_b32 s42, s34, s63
	v_lshl_add_u64 v[4:5], v[150:151], 0, s[40:41]
	s_add_i32 m0, s37, 0xc000
	s_nop 0
	global_load_lds_dwordx4 v[4:5], off
	ds_read_b128 v[186:189], v3 offset:2048
	ds_read_b128 v[190:193], v3 offset:3072
	ds_read_b128 v[194:197], v159
	ds_read_b128 v[198:201], v159 offset:1024
	ds_read_b128 v[202:205], v159 offset:2048
	ds_read_b128 v[206:209], v159 offset:3072
	v_lshl_add_u64 v[4:5], v[152:153], 0, s[40:41]
	s_add_i32 m0, s37, 0xe000
	s_nop 0
	global_load_lds_dwordx4 v[4:5], off
	ds_read_b128 v[210:213], v159 offset:4096
	ds_read_b128 v[214:217], v159 offset:5120
	ds_read_b128 v[218:221], v159 offset:6144
	ds_read_b128 v[222:225], v159 offset:7168
	s_waitcnt vmcnt(8)
	s_waitcnt lgkmcnt(0)
	s_barrier
	s_setprio 1
	s_waitcnt lgkmcnt(0)
	v_mfma_f32_16x16x32_bf16 v[130:133], v[160:163], v[194:197], v[130:133]
	v_mfma_f32_16x16x32_bf16 v[130:133], v[164:167], v[198:201], v[130:133]
	v_mfma_f32_16x16x32_bf16 v[126:129], v[174:177], v[198:201], v[126:129]
	v_mfma_f32_16x16x32_bf16 v[126:129], v[168:171], v[194:197], v[126:129]
	v_mfma_f32_16x16x32_bf16 v[110:113], v[168:171], v[202:205], v[110:113]
	v_mfma_f32_16x16x32_bf16 v[110:113], v[174:177], v[206:209], v[110:113]
	v_mfma_f32_16x16x32_bf16 v[114:117], v[164:167], v[206:209], v[114:117]
	v_mfma_f32_16x16x32_bf16 v[114:117], v[160:163], v[202:205], v[114:117]
	v_mfma_f32_16x16x32_bf16 v[98:101], v[160:163], v[210:213], v[98:101]
	v_mfma_f32_16x16x32_bf16 v[98:101], v[164:167], v[214:217], v[98:101]
	v_mfma_f32_16x16x32_bf16 v[94:97], v[174:177], v[214:217], v[94:97]
	v_mfma_f32_16x16x32_bf16 v[94:97], v[168:171], v[210:213], v[94:97]
	v_mfma_f32_16x16x32_bf16 v[78:81], v[168:171], v[218:221], v[78:81]
	v_mfma_f32_16x16x32_bf16 v[78:81], v[174:177], v[222:225], v[78:81]
	v_mfma_f32_16x16x32_bf16 v[82:85], v[164:167], v[222:225], v[82:85]
	v_mfma_f32_16x16x32_bf16 v[82:85], v[160:163], v[218:221], v[82:85]
	s_setprio 0
	s_setprio 1
	v_mfma_f32_16x16x32_bf16 v[122:125], v[178:181], v[194:197], v[122:125]
	v_mfma_f32_16x16x32_bf16 v[122:125], v[182:185], v[198:201], v[122:125]
	v_mfma_f32_16x16x32_bf16 v[118:121], v[190:193], v[198:201], v[118:121]
	v_mfma_f32_16x16x32_bf16 v[118:121], v[186:189], v[194:197], v[118:121]
	v_mfma_f32_16x16x32_bf16 v[102:105], v[186:189], v[202:205], v[102:105]
	v_mfma_f32_16x16x32_bf16 v[102:105], v[190:193], v[206:209], v[102:105]
	v_mfma_f32_16x16x32_bf16 v[106:109], v[182:185], v[206:209], v[106:109]
	v_mfma_f32_16x16x32_bf16 v[106:109], v[178:181], v[202:205], v[106:109]
	v_mfma_f32_16x16x32_bf16 v[90:93], v[178:181], v[210:213], v[90:93]
	v_mfma_f32_16x16x32_bf16 v[90:93], v[182:185], v[214:217], v[90:93]
	v_mfma_f32_16x16x32_bf16 v[86:89], v[190:193], v[214:217], v[86:89]
	v_mfma_f32_16x16x32_bf16 v[86:89], v[186:189], v[210:213], v[86:89]
	v_mfma_f32_16x16x32_bf16 v[70:73], v[186:189], v[218:221], v[70:73]
	v_mfma_f32_16x16x32_bf16 v[70:73], v[190:193], v[222:225], v[70:73]
	v_mfma_f32_16x16x32_bf16 v[74:77], v[182:185], v[222:225], v[74:77]
	v_mfma_f32_16x16x32_bf16 v[74:77], v[178:181], v[218:221], v[74:77]
	s_setprio 0
	s_barrier
	ds_read_b128 v[194:197], v159 offset:16384
	ds_read_b128 v[198:201], v159 offset:17408
	s_add_i32 s2, s55, s4
	v_lshl_add_u64 v[226:227], s[42:43], 0, v[136:137]
	s_mov_b32 m0, s2
	s_nop 0
	global_load_lds_dwordx4 v[226:227], off
	ds_read_b128 v[202:205], v159 offset:18432
	ds_read_b128 v[206:209], v159 offset:19456
	s_add_i32 m0, s2, 0x2000
	v_lshl_add_u64 v[228:229], s[42:43], 0, v[140:141]
	global_load_lds_dwordx4 v[228:229], off
	ds_read_b128 v[210:213], v159 offset:20480
	ds_read_b128 v[214:217], v159 offset:21504
	s_add_u32 s64, s42, 0x80000
	s_addc_u32 s65, s43, 0
	s_add_i32 s2, s56, s4
	v_lshl_add_u64 v[4:5], s[64:65], 0, v[136:137]
	s_mov_b32 m0, s2
	s_nop 0
	global_load_lds_dwordx4 v[4:5], off
	ds_read_b128 v[218:221], v159 offset:22528
	ds_read_b128 v[222:225], v159 offset:23552
	v_lshl_add_u64 v[4:5], s[64:65], 0, v[140:141]
	s_add_i32 m0, s2, 0x2000
	s_nop 0
	global_load_lds_dwordx4 v[4:5], off
	v_lshl_add_u64 v[230:231], s[44:45], 0, v[134:135]
	s_mov_b32 m0, s37
	s_nop 0
	global_load_lds_dwordx4 v[230:231], off
	v_lshl_add_u64 v[232:233], s[44:45], 0, v[138:139]
	s_mov_b32 m0, s48
	s_nop 0
	global_load_lds_dwordx4 v[232:233], off
	s_waitcnt vmcnt(8)
	s_waitcnt lgkmcnt(0)
	s_barrier
; #define PG8_STAGE(bufoff, gbase, voff) do { _Pragma("unroll") for (int _i = 0; _i < 2; ++_i) \
;         __builtin_amdgcn_global_load_lds((const unsigned*)((const char*)(gbase) + (voff)[_i]), (PG8_LAS unsigned*)(lds + (bufoff) + ldsw + _i * 8192), 16, 0, 0); } while (0)
; #define PG8_LDA(dst, b, h) do { _Pragma("unroll") for (int m = 0; m < 4; ++m) _Pragma("unroll") for (int k = 0; k < 2; ++k) dst[m][k] = *(const PG8_LAS bf16x8*)(lds + PG8_SA(b, h) + aoff + m * 2048 + k * 1024); } while (0)
; #define PG8_LDB(dst, b, h) do { _Pragma("unroll") for (int n = 0; n < 2; ++n) _Pragma("unroll") for (int k = 0; k < 2; ++k) dst[n][k] = *(const PG8_LAS bf16x8*)(lds + PG8_SB(b, h) + boff + n * 2048 + k * 1024); } while (0)
; #define PG8_MMA(ai, bj, At, Bt) do { __builtin_amdgcn_s_setprio(1); _Pragma("unroll") for (int m = 0; m < 4; ++m) _Pragma("unroll") for (int n = 0; n < 2; ++n) _Pragma("unroll") for (int k = 0; k < 2; ++k) \
;         acc[ai][bj][m][n] = __builtin_amdgcn_mfma_f32_16x16x32_bf16(Bt[n][k], At[m][k], acc[ai][bj][m][n], 0, 0, 0); __builtin_amdgcn_s_setprio(0); } while (0)
; #define PG8_WAIT_V(n) asm volatile("s_waitcnt vmcnt(" #n ")" ::: "memory")
; #define PG8_WAIT_L(n) asm volatile("s_waitcnt lgkmcnt(" #n ")" ::: "memory")
; #define PG8_BAR __builtin_amdgcn_s_barrier()
; template <class Epi, class Sched, bool ALIGN_EPI>
; __device__ __forceinline__ void gemm_phase(PG8_LAS unsigned char* lds, const Gemm g, const Sched& S, const Epi& E) {
;     ...
;             PG8_WAIT_V(8); PG8_WAIT_L(0); PG8_BAR; PG8_MMA(0, 0, At, B0); PG8_MMA(0, 1, At, B1); PG8_BAR; PG8_SCHED;
;             PG8_LDA(At, 0, 1); PG8_STAGE(PG8_SB(0, 0), b2, voffB); PG8_STAGE(PG8_SB(0, 1), b2 + hstepB, voffB); PG8_STAGE(PG8_SA(0, 0), a2, voffA);
;             PG8_WAIT_V(8); PG8_WAIT_L(0); PG8_BAR; PG8_MMA(1, 0, At, B0); PG8_MMA(1, 1, At, B1); PG8_BAR; PG8_SCHED;
;             PG8_LDB(B0, 1, 0); PG8_LDB(B1, 1, 1); PG8_SCHED; PG8_LDA(At, 1, 0); PG8_STAGE(PG8_SA(0, 1), a2 + hstepA, voffA);
;             PG8_WAIT_V(8); PG8_WAIT_L(0); PG8_BAR; PG8_MMA(0, 0, At, B0); PG8_MMA(0, 1, At, B1); PG8_BAR; PG8_SCHED;
;             PG8_LDA(At, 1, 1); PG8_STAGE(PG8_SB(1, 0), b3, voffB); PG8_STAGE(PG8_SB(1, 1), b3 + hstepB, voffB); PG8_STAGE(PG8_SA(1, 0), a3, voffA);
;             PG8_WAIT_V(8); PG8_WAIT_L(0); PG8_BAR; PG8_MMA(1, 0, At, B0); PG8_MMA(1, 1, At, B1); PG8_BAR; PG8_SCHED;
	s_setprio 1
	s_waitcnt lgkmcnt(0)
	v_mfma_f32_16x16x32_bf16 v[66:69], v[160:163], v[194:197], v[66:69]
	v_mfma_f32_16x16x32_bf16 v[66:69], v[164:167], v[198:201], v[66:69]
	v_mfma_f32_16x16x32_bf16 v[62:65], v[174:177], v[198:201], v[62:65]
	v_mfma_f32_16x16x32_bf16 v[62:65], v[168:171], v[194:197], v[62:65]
	v_mfma_f32_16x16x32_bf16 v[46:49], v[168:171], v[202:205], v[46:49]
	v_mfma_f32_16x16x32_bf16 v[46:49], v[174:177], v[206:209], v[46:49]
	v_mfma_f32_16x16x32_bf16 v[50:53], v[164:167], v[206:209], v[50:53]
	v_mfma_f32_16x16x32_bf16 v[50:53], v[160:163], v[202:205], v[50:53]
	v_mfma_f32_16x16x32_bf16 v[34:37], v[160:163], v[210:213], v[34:37]
	v_mfma_f32_16x16x32_bf16 v[34:37], v[164:167], v[214:217], v[34:37]
	v_mfma_f32_16x16x32_bf16 v[30:33], v[174:177], v[214:217], v[30:33]
	v_mfma_f32_16x16x32_bf16 v[30:33], v[168:171], v[210:213], v[30:33]
	v_mfma_f32_16x16x32_bf16 v[14:17], v[168:171], v[218:221], v[14:17]
	v_mfma_f32_16x16x32_bf16 v[14:17], v[174:177], v[222:225], v[14:17]
	v_mfma_f32_16x16x32_bf16 v[18:21], v[164:167], v[222:225], v[18:21]
	v_mfma_f32_16x16x32_bf16 v[18:21], v[160:163], v[218:221], v[18:21]
	s_setprio 0
	s_setprio 1
	v_mfma_f32_16x16x32_bf16 v[58:61], v[178:181], v[194:197], v[58:61]
	v_mfma_f32_16x16x32_bf16 v[54:57], v[186:189], v[194:197], v[54:57]
	v_mfma_f32_16x16x32_bf16 v[42:45], v[178:181], v[202:205], v[42:45]
	v_mfma_f32_16x16x32_bf16 v[38:41], v[186:189], v[202:205], v[38:41]
	v_mfma_f32_16x16x32_bf16 v[26:29], v[178:181], v[210:213], v[26:29]
	v_mfma_f32_16x16x32_bf16 v[22:25], v[186:189], v[210:213], v[22:25]
	v_mfma_f32_16x16x32_bf16 v[10:13], v[178:181], v[218:221], v[10:13]
	v_mfma_f32_16x16x32_bf16 v[4:7], v[186:189], v[218:221], v[6:9]
	v_mfma_f32_16x16x32_bf16 v[58:61], v[182:185], v[198:201], v[58:61]
	v_mfma_f32_16x16x32_bf16 v[54:57], v[190:193], v[198:201], v[54:57]
	v_mfma_f32_16x16x32_bf16 v[42:45], v[182:185], v[206:209], v[42:45]
	v_mfma_f32_16x16x32_bf16 v[38:41], v[190:193], v[206:209], v[38:41]
	v_mfma_f32_16x16x32_bf16 v[26:29], v[182:185], v[214:217], v[26:29]
	v_mfma_f32_16x16x32_bf16 v[22:25], v[190:193], v[214:217], v[22:25]
	v_mfma_f32_16x16x32_bf16 v[10:13], v[182:185], v[222:225], v[10:13]
	v_mfma_f32_16x16x32_bf16 v[4:7], v[190:193], v[222:225], v[4:7]
	s_setprio 0
	s_barrier
	s_add_i32 s2, 0, 0x18000
	v_add_u32_e32 v3, s2, v155
	ds_read_b128 v[160:163], v3
	ds_read_b128 v[164:167], v3 offset:1024
	ds_read_b128 v[168:171], v3 offset:2048
	ds_read_b128 v[174:177], v3 offset:3072
	s_add_i32 s63, 0, 0x1c000
	v_add_u32_e32 v3, s63, v155
	ds_read_b128 v[178:181], v3
	ds_read_b128 v[182:185], v3 offset:1024
	s_add_u32 s44, s44, 0x80000
	s_addc_u32 s45, s45, 0
	s_mov_b32 m0, s49
	v_lshl_add_u64 v[8:9], s[44:45], 0, v[134:135]
	global_load_lds_dwordx4 v[8:9], off
	ds_read_b128 v[186:189], v3 offset:2048
	ds_read_b128 v[190:193], v3 offset:3072
	ds_read_b128 v[194:197], v159 offset:32768
	ds_read_b128 v[198:201], v159 offset:33792
	ds_read_b128 v[202:205], v159 offset:34816
	ds_read_b128 v[206:209], v159 offset:35840
	v_lshl_add_u64 v[8:9], s[44:45], 0, v[138:139]
	s_mov_b32 m0, s50
	s_nop 0
	global_load_lds_dwordx4 v[8:9], off
	ds_read_b128 v[210:213], v159 offset:36864
	ds_read_b128 v[214:217], v159 offset:37888
	ds_read_b128 v[218:221], v159 offset:38912
	ds_read_b128 v[222:225], v159 offset:39936
	s_waitcnt vmcnt(8)
	s_waitcnt lgkmcnt(0)
	s_barrier
	s_setprio 1
	s_waitcnt lgkmcnt(0)
	v_mfma_f32_16x16x32_bf16 v[130:133], v[160:163], v[194:197], v[130:133]
	v_mfma_f32_16x16x32_bf16 v[130:133], v[164:167], v[198:201], v[130:133]
	v_mfma_f32_16x16x32_bf16 v[126:129], v[174:177], v[198:201], v[126:129]
	v_mfma_f32_16x16x32_bf16 v[126:129], v[168:171], v[194:197], v[126:129]
	v_mfma_f32_16x16x32_bf16 v[110:113], v[168:171], v[202:205], v[110:113]
	v_mfma_f32_16x16x32_bf16 v[110:113], v[174:177], v[206:209], v[110:113]
	v_mfma_f32_16x16x32_bf16 v[114:117], v[164:167], v[206:209], v[114:117]
	v_mfma_f32_16x16x32_bf16 v[114:117], v[160:163], v[202:205], v[114:117]
	v_mfma_f32_16x16x32_bf16 v[98:101], v[160:163], v[210:213], v[98:101]
	v_mfma_f32_16x16x32_bf16 v[98:101], v[164:167], v[214:217], v[98:101]
	v_mfma_f32_16x16x32_bf16 v[94:97], v[174:177], v[214:217], v[94:97]
	v_mfma_f32_16x16x32_bf16 v[94:97], v[168:171], v[210:213], v[94:97]
	v_mfma_f32_16x16x32_bf16 v[78:81], v[168:171], v[218:221], v[78:81]
	v_mfma_f32_16x16x32_bf16 v[78:81], v[174:177], v[222:225], v[78:81]
	v_mfma_f32_16x16x32_bf16 v[82:85], v[164:167], v[222:225], v[82:85]
	v_mfma_f32_16x16x32_bf16 v[82:85], v[160:163], v[218:221], v[82:85]
	s_setprio 0
	s_setprio 1
	v_mfma_f32_16x16x32_bf16 v[122:125], v[178:181], v[194:197], v[122:125]
	v_mfma_f32_16x16x32_bf16 v[122:125], v[182:185], v[198:201], v[122:125]
	v_mfma_f32_16x16x32_bf16 v[118:121], v[190:193], v[198:201], v[118:121]
	v_mfma_f32_16x16x32_bf16 v[118:121], v[186:189], v[194:197], v[118:121]
	v_mfma_f32_16x16x32_bf16 v[102:105], v[186:189], v[202:205], v[102:105]
	v_mfma_f32_16x16x32_bf16 v[102:105], v[190:193], v[206:209], v[102:105]
	v_mfma_f32_16x16x32_bf16 v[106:109], v[182:185], v[206:209], v[106:109]
	v_mfma_f32_16x16x32_bf16 v[106:109], v[178:181], v[202:205], v[106:109]
	v_mfma_f32_16x16x32_bf16 v[90:93], v[178:181], v[210:213], v[90:93]
	v_mfma_f32_16x16x32_bf16 v[90:93], v[182:185], v[214:217], v[90:93]
	v_mfma_f32_16x16x32_bf16 v[86:89], v[190:193], v[214:217], v[86:89]
	v_mfma_f32_16x16x32_bf16 v[86:89], v[186:189], v[210:213], v[86:89]
	v_mfma_f32_16x16x32_bf16 v[70:73], v[186:189], v[218:221], v[70:73]
	v_mfma_f32_16x16x32_bf16 v[70:73], v[190:193], v[222:225], v[70:73]
	v_mfma_f32_16x16x32_bf16 v[74:77], v[182:185], v[222:225], v[74:77]
	v_mfma_f32_16x16x32_bf16 v[74:77], v[178:181], v[218:221], v[74:77]
	s_setprio 0
	s_barrier
; #define PG8_STAGE(bufoff, gbase, voff) do { _Pragma("unroll") for (int _i = 0; _i < 2; ++_i) \
;         __builtin_amdgcn_global_load_lds((const unsigned*)((const char*)(gbase) + (voff)[_i]), (PG8_LAS unsigned*)(lds + (bufoff) + ldsw + _i * 8192), 16, 0, 0); } while (0)
; #define PG8_LDA(dst, b, h) do { _Pragma("unroll") for (int m = 0; m < 4; ++m) _Pragma("unroll") for (int k = 0; k < 2; ++k) dst[m][k] = *(const PG8_LAS bf16x8*)(lds + PG8_SA(b, h) + aoff + m * 2048 + k * 1024); } while (0)
; #define PG8_MMA(ai, bj, At, Bt) do { __builtin_amdgcn_s_setprio(1); _Pragma("unroll") for (int m = 0; m < 4; ++m) _Pragma("unroll") for (int n = 0; n < 2; ++n) _Pragma("unroll") for (int k = 0; k < 2; ++k) \
;         acc[ai][bj][m][n] = __builtin_amdgcn_mfma_f32_16x16x32_bf16(Bt[n][k], At[m][k], acc[ai][bj][m][n], 0, 0, 0); __builtin_amdgcn_s_setprio(0); } while (0)
; #define PG8_WAIT_V(n) asm volatile("s_waitcnt vmcnt(" #n ")" ::: "memory")
; #define PG8_WAIT_L(n) asm volatile("s_waitcnt lgkmcnt(" #n ")" ::: "memory")
; #define PG8_BAR __builtin_amdgcn_s_barrier()
; #define PG8_SCHED __builtin_amdgcn_sched_barrier(0)
; template <class Epi, class Sched, bool ALIGN_EPI>
; __device__ __forceinline__ void gemm_phase(PG8_LAS unsigned char* lds, const Gemm g, const Sched& S, const Epi& E) {
;     ...
;         for (int t = 0; t < nt; t += 2) {
;     ...
;             PG8_LDA(At, 1, 1); PG8_STAGE(PG8_SB(1, 0), b3, voffB); PG8_STAGE(PG8_SB(1, 1), b3 + hstepB, voffB); PG8_STAGE(PG8_SA(1, 0), a3, voffA);
;             PG8_WAIT_V(8); PG8_WAIT_L(0); PG8_BAR; PG8_MMA(1, 0, At, B0); PG8_MMA(1, 1, At, B1); PG8_BAR; PG8_SCHED;
	ds_read_b128 v[194:197], v159 offset:49152
	ds_read_b128 v[198:201], v159 offset:50176
	s_add_i32 s2, s2, s4
	v_lshl_add_u64 v[8:9], v[226:227], 0, s[16:17]
	s_mov_b32 m0, s2
	s_nop 0
	global_load_lds_dwordx4 v[8:9], off
	ds_read_b128 v[202:205], v159 offset:51200
	ds_read_b128 v[206:209], v159 offset:52224
	s_add_i32 m0, s2, 0x2000
	v_lshl_add_u64 v[8:9], v[228:229], 0, s[16:17]
	global_load_lds_dwordx4 v[8:9], off
	ds_read_b128 v[210:213], v159 offset:53248
	ds_read_b128 v[214:217], v159 offset:54272
	s_add_u32 s42, s42, 0x80080
	s_addc_u32 s43, s43, 0
	s_add_i32 s2, s63, s4
	v_lshl_add_u64 v[8:9], s[42:43], 0, v[136:137]
	s_mov_b32 m0, s2
	s_nop 0
	global_load_lds_dwordx4 v[8:9], off
	ds_read_b128 v[218:221], v159 offset:55296
	ds_read_b128 v[222:225], v159 offset:56320
	v_lshl_add_u64 v[8:9], s[42:43], 0, v[140:141]
	s_add_i32 m0, s2, 0x2000
	s_nop 0
	global_load_lds_dwordx4 v[8:9], off
	v_lshl_add_u64 v[8:9], v[230:231], 0, s[16:17]
	s_mov_b32 m0, s52
	s_nop 0
	global_load_lds_dwordx4 v[8:9], off
	v_lshl_add_u64 v[8:9], v[232:233], 0, s[16:17]
	s_mov_b32 m0, s53
	s_nop 0
	global_load_lds_dwordx4 v[8:9], off
	s_waitcnt vmcnt(8)
	s_waitcnt lgkmcnt(0)
	s_barrier
	s_setprio 1
	s_waitcnt lgkmcnt(0)
	v_mfma_f32_16x16x32_bf16 v[66:69], v[160:163], v[194:197], v[66:69]
	v_mfma_f32_16x16x32_bf16 v[66:69], v[164:167], v[198:201], v[66:69]
	v_mfma_f32_16x16x32_bf16 v[62:65], v[174:177], v[198:201], v[62:65]
	v_mfma_f32_16x16x32_bf16 v[62:65], v[168:171], v[194:197], v[62:65]
	v_mfma_f32_16x16x32_bf16 v[46:49], v[168:171], v[202:205], v[46:49]
	v_mfma_f32_16x16x32_bf16 v[46:49], v[174:177], v[206:209], v[46:49]
	v_mfma_f32_16x16x32_bf16 v[50:53], v[164:167], v[206:209], v[50:53]
	v_mfma_f32_16x16x32_bf16 v[50:53], v[160:163], v[202:205], v[50:53]
	v_mfma_f32_16x16x32_bf16 v[34:37], v[160:163], v[210:213], v[34:37]
	v_mfma_f32_16x16x32_bf16 v[34:37], v[164:167], v[214:217], v[34:37]
	v_mfma_f32_16x16x32_bf16 v[30:33], v[174:177], v[214:217], v[30:33]
	v_mfma_f32_16x16x32_bf16 v[30:33], v[168:171], v[210:213], v[30:33]
	v_mfma_f32_16x16x32_bf16 v[14:17], v[168:171], v[218:221], v[14:17]
	v_mfma_f32_16x16x32_bf16 v[14:17], v[174:177], v[222:225], v[14:17]
	v_mfma_f32_16x16x32_bf16 v[18:21], v[164:167], v[222:225], v[18:21]
	v_mfma_f32_16x16x32_bf16 v[18:21], v[160:163], v[218:221], v[18:21]
	s_setprio 0
	s_setprio 1
	v_mfma_f32_16x16x32_bf16 v[58:61], v[178:181], v[194:197], v[58:61]
	v_mfma_f32_16x16x32_bf16 v[54:57], v[186:189], v[194:197], v[54:57]
	v_mfma_f32_16x16x32_bf16 v[42:45], v[178:181], v[202:205], v[42:45]
	v_mfma_f32_16x16x32_bf16 v[38:41], v[186:189], v[202:205], v[38:41]
	v_mfma_f32_16x16x32_bf16 v[26:29], v[178:181], v[210:213], v[26:29]
	v_mfma_f32_16x16x32_bf16 v[22:25], v[186:189], v[210:213], v[22:25]
	v_mfma_f32_16x16x32_bf16 v[8:11], v[178:181], v[218:221], v[10:13]
	v_mfma_f32_16x16x32_bf16 v[4:7], v[186:189], v[218:221], v[4:7]
	v_mfma_f32_16x16x32_bf16 v[58:61], v[182:185], v[198:201], v[58:61]
	v_mfma_f32_16x16x32_bf16 v[54:57], v[190:193], v[198:201], v[54:57]
	v_mfma_f32_16x16x32_bf16 v[42:45], v[182:185], v[206:209], v[42:45]
	v_mfma_f32_16x16x32_bf16 v[38:41], v[190:193], v[206:209], v[38:41]
	v_mfma_f32_16x16x32_bf16 v[26:29], v[182:185], v[214:217], v[26:29]
	v_mfma_f32_16x16x32_bf16 v[22:25], v[190:193], v[214:217], v[22:25]
	v_mfma_f32_16x16x32_bf16 v[10:13], v[182:185], v[222:225], v[8:11]
	v_mfma_f32_16x16x32_bf16 v[6:9], v[190:193], v[222:225], v[4:7]
	s_setprio 0
	s_barrier
	s_add_i32 s62, s62, 2
	s_add_u32 s40, s40, 0x100
	s_addc_u32 s41, s41, 0
	s_cmp_gt_u32 s62, 29
	s_cbranch_scc1 .LBB0_842
